# out-proj/ff1 context tiles: K-slice 1 requested before waiting for K-slice 0 (counted vmcnt(8)), one exposed LDS-DMA round trip less per tile; on v189
# speedup vs baseline: 1.0104x; 1.0104x over previous
; #define WAIT_V0() asm volatile("s_waitcnt vmcnt(0)" ::: "memory")
; template <int EK, int TS, int KS>
; DI void ctx_tiles(const Params& p, int l, const bf16_t* __restrict__ A, const bf16_t* __restrict__ Bt, int N, int K, ldsp_t shm) {
;     ...
;         const int tm = u / ntn, tn = u % ntn;
;         int tid = threadIdx.x;
;         asm volatile("" : "+v"(tid));
;         const int wid = tid >> 6, lane = tid & 63, wr = wid >> 2, wc = wid & 3, fr = lane & 15, fq = lane >> 4;
;         unsigned soff[PP];
; #pragma unroll
;         for (int i = 0; i < PP; ++i) { int sR, sC; stage_rc_ks<KS>((wid * PP + i) * 1024 + lane * 16, sR, sC); soff[i] = (unsigned)(sR * K + sC) * 2u; }
;         const bf16_t* Ab = A + (size_t)tm * TS * K;
;         const bf16_t* Bb = Bt + (size_t)tn * TS * K;
;     ...
;         f32x4 acc[MT][NT];
; #pragma unroll
;         for (int m = 0; m < MT; ++m)
; #pragma unroll
;             for (int n = 0; n < NT; ++n) acc[m][n] = (f32x4){0.f, 0.f, 0.f, 0.f};
;         const int aoff = lds_byte_ks<KS>(wr * WM + fr, fq * 8), boff = lds_byte_ks<KS>(wc * WN + fr, fq * 8);
;         C_STAGE(0, 0); WAIT_V0(); __syncthreads();
;         for (int t = 0; t < nt; ++t) {
;             const int cur = t & 1;
;             if (t + 1 < nt) C_STAGE(cur ^ 1, t + 1);
.LBB0_119:
	v_mov_b32_e32 v32, v252
	s_ashr_i32 s10, s31, 31
	v_ashrrev_i32_e32 v0, 6, v32
	v_lshlrev_b32_e32 v25, 12, v0
	v_lshlrev_b32_e32 v1, 4, v32
	v_and_b32_e32 v2, 32, v32
	v_bitop3_b32 v1, v1, v2, 48 bitop3:0x6c
	v_lshlrev_b32_e32 v2, 9, v32
	s_waitcnt lgkmcnt(5)
	v_or_b32_e32 v4, 0x400, v25
	v_and_or_b32 v1, v2, s20, v1
	v_ashrrev_i32_e32 v2, 10, v4
	v_ashrrev_i32_e32 v3, 31, v2
	v_lshrrev_b32_e32 v3, 30, v3
	v_add_u32_e32 v3, v2, v3
	s_waitcnt lgkmcnt(0)
	v_and_b32_e32 v5, 0x3fffffc, v3
	v_lshlrev_b32_e32 v3, 13, v3
	v_sub_u32_e32 v2, v2, v5
	v_and_or_b32 v3, v3, s90, v1
	v_or_b32_e32 v14, 0x800, v25
	v_lshl_add_u32 v8, v2, 6, v3
	v_ashrrev_i32_e32 v2, 10, v14
	v_ashrrev_i32_e32 v3, 31, v2
	v_lshrrev_b32_e32 v3, 30, v3
	s_lshr_b32 s10, s10, 27
	v_add_u32_e32 v3, v2, v3
	s_add_i32 s10, s31, s10
	v_and_b32_e32 v5, 0x3fffffc, v3
	v_lshlrev_b32_e32 v3, 13, v3
	s_ashr_i32 s34, s10, 5
	v_sub_u32_e32 v2, v2, v5
	v_and_or_b32 v3, v3, s90, v1
	v_or_b32_e32 v18, 0xc00, v25
	s_andn2_b32 s10, s10, 31
	v_lshl_add_u32 v12, v2, 6, v3
	v_ashrrev_i32_e32 v2, 10, v18
	s_sub_i32 s36, s31, s10
	v_ashrrev_i32_e32 v3, 31, v2
	s_ashr_i32 s35, s34, 31
	s_ashr_i32 s37, s36, 31
	v_lshrrev_b32_e32 v3, 30, v3
	s_lshl_b64 s[10:11], s[34:35], 18
	s_lshl_b64 s[38:39], s[36:37], 18
	v_add_u32_e32 v3, v2, v3
	s_add_u32 s40, s8, s10
	v_and_b32_e32 v5, 0x3fffffc, v3
	s_addc_u32 s41, s14, s11
	v_sub_u32_e32 v2, v2, v5
	s_add_u32 s38, s9, s38
	v_readfirstlane_b32 s11, v25
	v_add_u32_e32 v5, 0x8000, v25
	v_lshl_or_b32 v192, v0, 15, v1
	s_addc_u32 s39, s45, s39
	s_mov_b32 m0, s11
	v_readfirstlane_b32 s10, v5
	v_mov_b32_e32 v9, v193
	global_load_lds_dwordx4 v192, s[40:41]
	s_mov_b32 m0, s10
	v_lshl_add_u64 v[6:7], s[40:41], 0, v[8:9]
	v_readfirstlane_b32 s37, v4
	v_lshl_add_u64 v[4:5], s[38:39], 0, v[8:9]
	v_add_u32_e32 v9, 0x8400, v25
	global_load_lds_dwordx4 v192, s[38:39]
	s_mov_b32 m0, s37
	v_readfirstlane_b32 s35, v9
	global_load_lds_dwordx4 v8, s[40:41]
	s_mov_b32 m0, s35
	v_mov_b32_e32 v13, v193
	v_lshlrev_b32_e32 v3, 13, v3
	global_load_lds_dwordx4 v8, s[38:39]
	v_lshl_add_u64 v[10:11], s[40:41], 0, v[12:13]
	v_readfirstlane_b32 s43, v14
	v_lshl_add_u64 v[8:9], s[38:39], 0, v[12:13]
	v_add_u32_e32 v13, 0x8800, v25
	v_and_or_b32 v1, v3, s90, v1
	s_mov_b32 m0, s43
	v_readfirstlane_b32 s42, v13
	v_lshl_add_u32 v16, v2, 6, v1
	global_load_lds_dwordx4 v12, s[40:41]
	s_mov_b32 m0, s42
	v_mov_b32_e32 v17, v193
	v_readfirstlane_b32 s46, v18
	global_load_lds_dwordx4 v12, s[38:39]
	v_lshl_add_u64 v[14:15], s[40:41], 0, v[16:17]
	s_mov_b32 m0, s46
	v_lshl_add_u64 v[12:13], s[38:39], 0, v[16:17]
	v_add_u32_e32 v17, 0x8c00, v25
	v_ashrrev_i32_e32 v1, 2, v32
	v_lshl_add_u64 v[2:3], s[40:41], 0, v[192:193]
	global_load_lds_dwordx4 v16, s[40:41]
	v_readfirstlane_b32 s40, v17
	v_and_b32_e32 v33, 15, v32
	v_and_b32_e32 v19, 0xffffffc0, v1
	v_and_b32_e32 v1, 48, v32
	v_lshlrev_b32_e32 v20, 5, v0
	v_lshlrev_b32_e32 v0, 2, v32
	s_mov_b32 m0, s40
	v_add_u32_e32 v18, 0x10000, v25
	v_or_b32_e32 v34, v19, v33
	v_lshl_or_b32 v26, v33, 6, v1
	v_and_b32_e32 v27, 32, v0
	v_lshl_add_u64 v[0:1], s[38:39], 0, v[192:193]
	global_load_lds_dwordx4 v16, s[38:39]
	v_lshlrev_b32_e32 v28, 8, v19
	v_readfirstlane_b32 s38, v18
	v_add_u32_e32 v19, 0x18000, v25
	v_and_b32_e32 v35, 0x60, v20
	v_lshl_add_u64 v[16:17], v[2:3], 0, s[96:97]
	s_mov_b32 m0, s38
	v_readfirstlane_b32 s41, v19
	v_add_u32_e32 v20, 0x10400, v25
	global_load_lds_dwordx4 v[16:17], off
	v_lshl_add_u64 v[16:17], v[0:1], 0, s[96:97]
	s_mov_b32 m0, s41
	v_readfirstlane_b32 s50, v20
	v_add_u32_e32 v21, 0x18400, v25
	global_load_lds_dwordx4 v[16:17], off
	v_lshl_add_u64 v[16:17], v[6:7], 0, s[96:97]
	s_mov_b32 m0, s50
	v_readfirstlane_b32 s47, v21
	v_add_u32_e32 v22, 0x10800, v25
	global_load_lds_dwordx4 v[16:17], off
	v_lshl_add_u64 v[16:17], v[4:5], 0, s[96:97]
	s_mov_b32 m0, s47
	v_readfirstlane_b32 s51, v22
	v_add_u32_e32 v23, 0x18800, v25
	global_load_lds_dwordx4 v[16:17], off
	v_lshl_add_u64 v[16:17], v[10:11], 0, s[96:97]
	s_mov_b32 m0, s51
	v_readfirstlane_b32 s85, v23
	v_add_u32_e32 v24, 0x10c00, v25
	global_load_lds_dwordx4 v[16:17], off
	v_lshl_add_u64 v[16:17], v[8:9], 0, s[96:97]
	s_mov_b32 m0, s85
	v_readfirstlane_b32 s84, v24
	v_add_u32_e32 v25, 0x18c00, v25
	global_load_lds_dwordx4 v[16:17], off
	v_lshl_add_u64 v[16:17], v[14:15], 0, s[96:97]
	s_mov_b32 m0, s84
	v_readfirstlane_b32 s39, v25
	global_load_lds_dwordx4 v[16:17], off
	v_lshl_add_u64 v[16:17], v[12:13], 0, s[96:97]
	s_mov_b32 m0, s39
	v_lshlrev_b32_e32 v29, 8, v35
	global_load_lds_dwordx4 v[16:17], off
	v_bitop3_b32 v16, v26, v28, v27 bitop3:0xde
	v_bitop3_b32 v17, v26, v29, v27 bitop3:0xde
	s_waitcnt vmcnt(8)
	s_waitcnt vmcnt(8) lgkmcnt(0)
	s_barrier
; #define LDSP __attribute__((address_space(3)))
; #define WAIT_V0() asm volatile("s_waitcnt vmcnt(0)" ::: "memory")
; template <int EK, int TS, int KS>
; DI void ctx_tiles(const Params& p, int l, const bf16_t* __restrict__ A, const bf16_t* __restrict__ Bt, int N, int K, ldsp_t shm) {
;     ...
;         for (int t = 0; t < nt; ++t) {
;             const int cur = t & 1;
;             if (t + 1 < nt) C_STAGE(cur ^ 1, t + 1);
;             ldsp_t sa = shm + cur * 2 * TILE_A, sb = sa + TILE_A;
; #pragma unroll
;             for (int ks = 0; ks < KS; ++ks) {
;                 bf16x8 At[MT], Bf[NT];
; #pragma unroll
;                 for (int m = 0; m < MT; ++m) At[m] = *(const LDSP bf16x8*)(sa + aoff + m * (KS * 1024) + ks * 1024);
; #pragma unroll
;                 for (int n = 0; n < NT; ++n) Bf[n] = *(const LDSP bf16x8*)(sb + boff + n * (KS * 1024) + ks * 1024);
; #pragma unroll
;                 for (int m = 0; m < MT; ++m)
; #pragma unroll
;                     for (int n = 0; n < NT; ++n) acc[m][n] = __builtin_amdgcn_mfma_f32_16x16x32_bf16(Bf[n], At[m], acc[m][n], 0, 0, 0);
;             }
;             WAIT_V0(); __syncthreads();
;         }
	ds_read_b128 v[26:29], v16
	ds_read_b128 v[36:39], v16 offset:4096
	ds_read_b128 v[40:43], v16 offset:8192
	ds_read_b128 v[44:47], v16 offset:12288
	ds_read_b128 v[48:51], v17 offset:32768
	ds_read_b128 v[52:55], v17 offset:36864
	s_waitcnt lgkmcnt(0)
	v_mfma_f32_16x16x32_bf16 v[56:59], v[48:51], v[26:29], 0
	s_mov_b32 m0, s11
	v_or_b32_e32 v30, 0x19400, v17
	v_or_b32_e32 v31, 0x18800, v17
	v_mfma_f32_16x16x32_bf16 v[26:29], v[52:55], v[26:29], 0
	v_lshlrev_b32_e32 v34, 9, v34
	v_mfma_f32_16x16x32_bf16 v[60:63], v[48:51], v[36:39], 0
	v_mfma_f32_16x16x32_bf16 v[36:39], v[52:55], v[36:39], 0
	v_mfma_f32_16x16x32_bf16 v[64:67], v[48:51], v[40:43], 0
	v_mfma_f32_16x16x32_bf16 v[40:43], v[52:55], v[40:43], 0
	v_mfma_f32_16x16x32_bf16 v[48:51], v[48:51], v[44:47], 0
	v_mfma_f32_16x16x32_bf16 v[44:47], v[52:55], v[44:47], 0
	ds_read_b128 v[52:55], v16 offset:1024
	ds_read_b128 v[68:71], v16 offset:5120
	ds_read_b128 v[72:75], v16 offset:9216
	ds_read_b128 v[76:79], v16 offset:13312
	ds_read_b128 v[80:83], v17 offset:33792
	ds_read_b128 v[84:87], v17 offset:37888
	s_waitcnt lgkmcnt(0)
	v_mfma_f32_16x16x32_bf16 v[56:59], v[80:83], v[52:55], v[56:59]
	v_mfma_f32_16x16x32_bf16 v[26:29], v[84:87], v[52:55], v[26:29]
	v_mfma_f32_16x16x32_bf16 v[52:55], v[80:83], v[68:71], v[60:63]
	v_mfma_f32_16x16x32_bf16 v[36:39], v[84:87], v[68:71], v[36:39]
	v_mfma_f32_16x16x32_bf16 v[60:63], v[80:83], v[72:75], v[64:67]
	v_mfma_f32_16x16x32_bf16 v[40:43], v[84:87], v[72:75], v[40:43]
	v_mfma_f32_16x16x32_bf16 v[48:51], v[80:83], v[76:79], v[48:51]
	v_mfma_f32_16x16x32_bf16 v[44:47], v[84:87], v[76:79], v[44:47]
	ds_read_b128 v[64:67], v16 offset:2048
	ds_read_b128 v[68:71], v16 offset:6144
	ds_read_b128 v[72:75], v16 offset:10240
	ds_read_b128 v[76:79], v16 offset:14336
	ds_read_b128 v[80:83], v17 offset:34816
	ds_read_b128 v[84:87], v17 offset:38912
	s_waitcnt lgkmcnt(0)
	v_mfma_f32_16x16x32_bf16 v[56:59], v[80:83], v[64:67], v[56:59]
	v_mfma_f32_16x16x32_bf16 v[26:29], v[84:87], v[64:67], v[26:29]
	v_mfma_f32_16x16x32_bf16 v[52:55], v[80:83], v[68:71], v[52:55]
	v_mfma_f32_16x16x32_bf16 v[36:39], v[84:87], v[68:71], v[36:39]
	v_mfma_f32_16x16x32_bf16 v[60:63], v[80:83], v[72:75], v[60:63]
	v_mfma_f32_16x16x32_bf16 v[40:43], v[84:87], v[72:75], v[40:43]
	v_mfma_f32_16x16x32_bf16 v[48:51], v[80:83], v[76:79], v[48:51]
	v_mfma_f32_16x16x32_bf16 v[44:47], v[84:87], v[76:79], v[44:47]
	ds_read_b128 v[64:67], v16 offset:3072
	ds_read_b128 v[68:71], v16 offset:7168
	ds_read_b128 v[72:75], v16 offset:11264
	ds_read_b128 v[76:79], v16 offset:15360
	ds_read_b128 v[80:83], v17 offset:35840
	ds_read_b128 v[84:87], v17 offset:39936
	s_waitcnt vmcnt(0)
	s_waitcnt vmcnt(0) lgkmcnt(0)
	v_mfma_f32_16x16x32_bf16 v[56:59], v[80:83], v[64:67], v[56:59]
	s_barrier
	v_mfma_f32_16x16x32_bf16 v[64:67], v[84:87], v[64:67], v[26:29]
	s_nop 2
	v_lshl_add_u64 v[26:27], v[2:3], 0, s[2:3]
	global_load_lds_dwordx4 v[26:27], off
	v_lshl_add_u64 v[26:27], v[0:1], 0, s[2:3]
	s_mov_b32 m0, s10
	v_or_b32_e32 v28, 0x19000, v17
	global_load_lds_dwordx4 v[26:27], off
	v_lshl_add_u64 v[26:27], v[6:7], 0, s[2:3]
	s_mov_b32 m0, s37
	v_mfma_f32_16x16x32_bf16 v[52:55], v[80:83], v[68:71], v[52:55]
	global_load_lds_dwordx4 v[26:27], off
	v_lshl_add_u64 v[26:27], v[4:5], 0, s[2:3]
	s_mov_b32 m0, s35
	v_mfma_f32_16x16x32_bf16 v[36:39], v[84:87], v[68:71], v[36:39]
	global_load_lds_dwordx4 v[26:27], off
	v_lshl_add_u64 v[26:27], v[10:11], 0, s[2:3]
	s_mov_b32 m0, s43
	v_mfma_f32_16x16x32_bf16 v[60:63], v[80:83], v[72:75], v[60:63]
	global_load_lds_dwordx4 v[26:27], off
	v_lshl_add_u64 v[26:27], v[8:9], 0, s[2:3]
	s_mov_b32 m0, s42
	v_mfma_f32_16x16x32_bf16 v[40:43], v[84:87], v[72:75], v[40:43]
	global_load_lds_dwordx4 v[26:27], off
	v_lshl_add_u64 v[26:27], v[14:15], 0, s[2:3]
	s_mov_b32 m0, s46
	v_mfma_f32_16x16x32_bf16 v[48:51], v[80:83], v[76:79], v[48:51]
	global_load_lds_dwordx4 v[26:27], off
	v_lshl_add_u64 v[26:27], v[12:13], 0, s[2:3]
	s_mov_b32 m0, s40
	v_mfma_f32_16x16x32_bf16 v[44:47], v[84:87], v[76:79], v[44:47]
	global_load_lds_dwordx4 v[26:27], off
	v_add_u32_e32 v26, 0x10000, v16
	v_or_b32_e32 v27, 0x18000, v17
	ds_read_b128 v[68:71], v26
	ds_read_b128 v[72:75], v26 offset:4096
	ds_read_b128 v[76:79], v26 offset:8192
	ds_read_b128 v[80:83], v26 offset:12288
	ds_read_b128 v[84:87], v27
	ds_read_b128 v[88:91], v28
	v_or_b32_e32 v29, 0x18400, v17
	s_waitcnt lgkmcnt(0)
	v_mfma_f32_16x16x32_bf16 v[56:59], v[84:87], v[68:71], v[56:59]
	s_mov_b32 m0, s38
	v_mfma_f32_16x16x32_bf16 v[64:67], v[88:91], v[68:71], v[64:67]
	v_mfma_f32_16x16x32_bf16 v[52:55], v[84:87], v[72:75], v[52:55]
	v_mfma_f32_16x16x32_bf16 v[36:39], v[88:91], v[72:75], v[36:39]
	v_mfma_f32_16x16x32_bf16 v[60:63], v[84:87], v[76:79], v[60:63]
	v_mfma_f32_16x16x32_bf16 v[40:43], v[88:91], v[76:79], v[40:43]
	v_mfma_f32_16x16x32_bf16 v[48:51], v[84:87], v[80:83], v[48:51]
	v_mfma_f32_16x16x32_bf16 v[44:47], v[88:91], v[80:83], v[44:47]
	ds_read_b128 v[68:71], v26 offset:1024
	ds_read_b128 v[72:75], v26 offset:5120
	ds_read_b128 v[76:79], v26 offset:9216
	ds_read_b128 v[80:83], v26 offset:13312
	ds_read_b128 v[84:87], v29
	ds_read_b128 v[88:91], v30
	s_waitcnt lgkmcnt(0)
	v_mfma_f32_16x16x32_bf16 v[56:59], v[84:87], v[68:71], v[56:59]
	v_mfma_f32_16x16x32_bf16 v[64:67], v[88:91], v[68:71], v[64:67]
	v_mfma_f32_16x16x32_bf16 v[68:71], v[88:91], v[72:75], v[36:39]
	s_nop 2
	v_or_b32_e32 v36, 0x19800, v17
	v_mfma_f32_16x16x32_bf16 v[52:55], v[84:87], v[72:75], v[52:55]
	v_or_b32_e32 v37, 0x18c00, v17
	v_mfma_f32_16x16x32_bf16 v[60:63], v[84:87], v[76:79], v[60:63]
	v_mfma_f32_16x16x32_bf16 v[38:41], v[88:91], v[76:79], v[40:43]
	v_mfma_f32_16x16x32_bf16 v[48:51], v[84:87], v[80:83], v[48:51]
	v_mfma_f32_16x16x32_bf16 v[42:45], v[88:91], v[80:83], v[44:47]
	ds_read_b128 v[72:75], v26 offset:2048
	ds_read_b128 v[76:79], v26 offset:6144
	ds_read_b128 v[80:83], v26 offset:10240
	ds_read_b128 v[84:87], v26 offset:14336
	ds_read_b128 v[88:91], v31
	ds_read_b128 v[92:95], v36
	s_waitcnt lgkmcnt(0)
	v_mfma_f32_16x16x32_bf16 v[56:59], v[88:91], v[72:75], v[56:59]
	v_mfma_f32_16x16x32_bf16 v[64:67], v[92:95], v[72:75], v[64:67]
	v_mfma_f32_16x16x32_bf16 v[52:55], v[88:91], v[76:79], v[52:55]
	v_mfma_f32_16x16x32_bf16 v[68:71], v[92:95], v[76:79], v[68:71]
	v_mfma_f32_16x16x32_bf16 v[60:63], v[88:91], v[80:83], v[60:63]
	v_mfma_f32_16x16x32_bf16 v[72:75], v[92:95], v[80:83], v[38:41]
	v_mfma_f32_16x16x32_bf16 v[46:49], v[88:91], v[84:87], v[48:51]
	s_nop 1
	v_or_b32_e32 v38, 0x19c00, v17
	v_mfma_f32_16x16x32_bf16 v[40:43], v[92:95], v[84:87], v[42:45]
	ds_read_b128 v[76:79], v26 offset:3072
	ds_read_b128 v[80:83], v26 offset:7168
	ds_read_b128 v[84:87], v26 offset:11264
	ds_read_b128 v[88:91], v26 offset:15360
	ds_read_b128 v[92:95], v37
	ds_read_b128 v[96:99], v38
	s_waitcnt lgkmcnt(0)
	v_mfma_f32_16x16x32_bf16 v[44:47], v[92:95], v[88:91], v[46:49]
	s_nop 2
	v_lshl_add_u64 v[48:49], v[2:3], 0, s[22:23]
	s_waitcnt vmcnt(0)
	s_waitcnt vmcnt(0)
	s_barrier
; #define LDSP __attribute__((address_space(3)))
; #define WAIT_V0() asm volatile("s_waitcnt vmcnt(0)" ::: "memory")
; template <int EK, int TS, int KS>
; DI void ctx_tiles(const Params& p, int l, const bf16_t* __restrict__ A, const bf16_t* __restrict__ Bt, int N, int K, ldsp_t shm) {
;     ...
;         for (int t = 0; t < nt; ++t) {
;             const int cur = t & 1;
;             if (t + 1 < nt) C_STAGE(cur ^ 1, t + 1);
;             ldsp_t sa = shm + cur * 2 * TILE_A, sb = sa + TILE_A;
; #pragma unroll
;             for (int ks = 0; ks < KS; ++ks) {
;                 bf16x8 At[MT], Bf[NT];
; #pragma unroll
;                 for (int m = 0; m < MT; ++m) At[m] = *(const LDSP bf16x8*)(sa + aoff + m * (KS * 1024) + ks * 1024);
; #pragma unroll
;                 for (int n = 0; n < NT; ++n) Bf[n] = *(const LDSP bf16x8*)(sb + boff + n * (KS * 1024) + ks * 1024);
; #pragma unroll
;                 for (int m = 0; m < MT; ++m)
; #pragma unroll
;                     for (int n = 0; n < NT; ++n) acc[m][n] = __builtin_amdgcn_mfma_f32_16x16x32_bf16(Bf[n], At[m], acc[m][n], 0, 0, 0);
;             }
;             WAIT_V0(); __syncthreads();
;         }
	global_load_lds_dwordx4 v[48:49], off
	v_lshl_add_u64 v[48:49], v[0:1], 0, s[22:23]
	s_mov_b32 m0, s41
	v_mfma_f32_16x16x32_bf16 v[56:59], v[92:95], v[76:79], v[56:59]
	global_load_lds_dwordx4 v[48:49], off
	v_lshl_add_u64 v[48:49], v[6:7], 0, s[22:23]
	s_mov_b32 m0, s50
	v_mfma_f32_16x16x32_bf16 v[64:67], v[96:99], v[76:79], v[64:67]
	global_load_lds_dwordx4 v[48:49], off
	v_lshl_add_u64 v[48:49], v[4:5], 0, s[22:23]
	s_mov_b32 m0, s47
	v_mfma_f32_16x16x32_bf16 v[50:53], v[92:95], v[80:83], v[52:55]
	global_load_lds_dwordx4 v[48:49], off
	v_lshl_add_u64 v[48:49], v[10:11], 0, s[22:23]
	s_mov_b32 m0, s51
	v_mfma_f32_16x16x32_bf16 v[68:71], v[96:99], v[80:83], v[68:71]
	global_load_lds_dwordx4 v[48:49], off
	v_lshl_add_u64 v[48:49], v[8:9], 0, s[22:23]
	s_mov_b32 m0, s85
	v_mfma_f32_16x16x32_bf16 v[60:63], v[92:95], v[84:87], v[60:63]
	global_load_lds_dwordx4 v[48:49], off
	v_lshl_add_u64 v[48:49], v[14:15], 0, s[22:23]
	s_mov_b32 m0, s84
	v_mfma_f32_16x16x32_bf16 v[72:75], v[96:99], v[84:87], v[72:75]
	global_load_lds_dwordx4 v[48:49], off
	v_lshl_add_u64 v[48:49], v[12:13], 0, s[22:23]
	s_mov_b32 m0, s39
	v_mfma_f32_16x16x32_bf16 v[40:43], v[96:99], v[88:91], v[40:43]
	global_load_lds_dwordx4 v[48:49], off
	ds_read_b128 v[76:79], v16
	ds_read_b128 v[80:83], v16 offset:4096
	ds_read_b128 v[84:87], v16 offset:8192
	ds_read_b128 v[88:91], v16 offset:12288
	ds_read_b128 v[92:95], v17 offset:32768
	ds_read_b128 v[96:99], v17 offset:36864
	s_waitcnt lgkmcnt(0)
	v_mfma_f32_16x16x32_bf16 v[54:57], v[92:95], v[76:79], v[56:59]
	s_mov_b32 m0, s11
	v_mfma_f32_16x16x32_bf16 v[64:67], v[96:99], v[76:79], v[64:67]
	v_mfma_f32_16x16x32_bf16 v[48:51], v[92:95], v[80:83], v[50:53]
	v_mfma_f32_16x16x32_bf16 v[68:71], v[96:99], v[80:83], v[68:71]
	v_mfma_f32_16x16x32_bf16 v[58:61], v[92:95], v[84:87], v[60:63]
	v_mfma_f32_16x16x32_bf16 v[72:75], v[96:99], v[84:87], v[72:75]
	v_mfma_f32_16x16x32_bf16 v[44:47], v[92:95], v[88:91], v[44:47]
	v_mfma_f32_16x16x32_bf16 v[40:43], v[96:99], v[88:91], v[40:43]
	ds_read_b128 v[76:79], v16 offset:1024
	ds_read_b128 v[80:83], v16 offset:5120
	ds_read_b128 v[84:87], v16 offset:9216
	ds_read_b128 v[88:91], v16 offset:13312
	ds_read_b128 v[92:95], v17 offset:33792
	ds_read_b128 v[96:99], v17 offset:37888
	s_waitcnt lgkmcnt(0)
	v_mfma_f32_16x16x32_bf16 v[52:55], v[92:95], v[76:79], v[54:57]
	v_mfma_f32_16x16x32_bf16 v[62:65], v[96:99], v[76:79], v[64:67]
	v_mfma_f32_16x16x32_bf16 v[48:51], v[92:95], v[80:83], v[48:51]
	v_mfma_f32_16x16x32_bf16 v[66:69], v[96:99], v[80:83], v[68:71]
	v_mfma_f32_16x16x32_bf16 v[56:59], v[92:95], v[84:87], v[58:61]
	v_mfma_f32_16x16x32_bf16 v[70:73], v[96:99], v[84:87], v[72:75]
	v_mfma_f32_16x16x32_bf16 v[44:47], v[92:95], v[88:91], v[44:47]
	v_mfma_f32_16x16x32_bf16 v[40:43], v[96:99], v[88:91], v[40:43]
	s_nop 0
	ds_read_b128 v[74:77], v16 offset:2048
	ds_read_b128 v[78:81], v16 offset:6144
	ds_read_b128 v[82:85], v16 offset:10240
	ds_read_b128 v[86:89], v16 offset:14336
	ds_read_b128 v[90:93], v17 offset:34816
	ds_read_b128 v[94:97], v17 offset:38912
	s_waitcnt lgkmcnt(0)
	v_mfma_f32_16x16x32_bf16 v[52:55], v[90:93], v[74:77], v[52:55]
	v_mfma_f32_16x16x32_bf16 v[60:63], v[94:97], v[74:77], v[62:65]
	v_mfma_f32_16x16x32_bf16 v[48:51], v[90:93], v[78:81], v[48:51]
	v_mfma_f32_16x16x32_bf16 v[64:67], v[94:97], v[78:81], v[66:69]
	v_mfma_f32_16x16x32_bf16 v[56:59], v[90:93], v[82:85], v[56:59]
	v_mfma_f32_16x16x32_bf16 v[68:71], v[94:97], v[82:85], v[70:73]
	v_mfma_f32_16x16x32_bf16 v[44:47], v[90:93], v[86:89], v[44:47]
	v_mfma_f32_16x16x32_bf16 v[40:43], v[94:97], v[86:89], v[40:43]
	s_nop 0
	ds_read_b128 v[72:75], v16 offset:3072
	ds_read_b128 v[76:79], v16 offset:7168
	ds_read_b128 v[80:83], v16 offset:11264
	ds_read_b128 v[84:87], v16 offset:15360
	ds_read_b128 v[88:91], v17 offset:35840
	ds_read_b128 v[92:95], v17 offset:39936
	s_waitcnt vmcnt(0)
	s_waitcnt vmcnt(0) lgkmcnt(0)
	v_mfma_f32_16x16x32_bf16 v[52:55], v[88:91], v[72:75], v[52:55]
	s_barrier
	v_mfma_f32_16x16x32_bf16 v[60:63], v[92:95], v[72:75], v[60:63]
	v_lshl_add_u64 v[72:73], v[2:3], 0, s[18:19]
	global_load_lds_dwordx4 v[72:73], off
	v_lshl_add_u64 v[72:73], v[0:1], 0, s[18:19]
	s_mov_b32 m0, s10
	v_mfma_f32_16x16x32_bf16 v[48:51], v[88:91], v[76:79], v[48:51]
	global_load_lds_dwordx4 v[72:73], off
	v_lshl_add_u64 v[72:73], v[6:7], 0, s[18:19]
	s_mov_b32 m0, s37
	v_mfma_f32_16x16x32_bf16 v[64:67], v[92:95], v[76:79], v[64:67]
	global_load_lds_dwordx4 v[72:73], off
	v_lshl_add_u64 v[72:73], v[4:5], 0, s[18:19]
	s_mov_b32 m0, s35
	v_mfma_f32_16x16x32_bf16 v[56:59], v[88:91], v[80:83], v[56:59]
	global_load_lds_dwordx4 v[72:73], off
	v_lshl_add_u64 v[72:73], v[10:11], 0, s[18:19]
	s_mov_b32 m0, s43
	v_mfma_f32_16x16x32_bf16 v[68:71], v[92:95], v[80:83], v[68:71]
	global_load_lds_dwordx4 v[72:73], off
	v_lshl_add_u64 v[72:73], v[8:9], 0, s[18:19]
	s_mov_b32 m0, s42
	v_mfma_f32_16x16x32_bf16 v[44:47], v[88:91], v[84:87], v[44:47]
	global_load_lds_dwordx4 v[72:73], off
	v_lshl_add_u64 v[72:73], v[14:15], 0, s[18:19]
	s_mov_b32 m0, s46
	v_mfma_f32_16x16x32_bf16 v[40:43], v[92:95], v[84:87], v[40:43]
	global_load_lds_dwordx4 v[72:73], off
	v_lshl_add_u64 v[72:73], v[12:13], 0, s[18:19]
	s_mov_b32 m0, s40
	s_nop 0
	global_load_lds_dwordx4 v[72:73], off
	ds_read_b128 v[72:75], v26
	ds_read_b128 v[76:79], v26 offset:4096
	ds_read_b128 v[80:83], v26 offset:8192
	ds_read_b128 v[84:87], v26 offset:12288
	ds_read_b128 v[88:91], v27
	ds_read_b128 v[92:95], v28
	s_waitcnt lgkmcnt(0)
; #define LDSP __attribute__((address_space(3)))
; #define WAIT_V0() asm volatile("s_waitcnt vmcnt(0)" ::: "memory")
; template <int EK, int TS, int KS>
; DI void ctx_tiles(const Params& p, int l, const bf16_t* __restrict__ A, const bf16_t* __restrict__ Bt, int N, int K, ldsp_t shm) {
;     ...
;         for (int t = 0; t < nt; ++t) {
;             const int cur = t & 1;
;             if (t + 1 < nt) C_STAGE(cur ^ 1, t + 1);
;             ldsp_t sa = shm + cur * 2 * TILE_A, sb = sa + TILE_A;
; #pragma unroll
;             for (int ks = 0; ks < KS; ++ks) {
;                 bf16x8 At[MT], Bf[NT];
; #pragma unroll
;                 for (int m = 0; m < MT; ++m) At[m] = *(const LDSP bf16x8*)(sa + aoff + m * (KS * 1024) + ks * 1024);
; #pragma unroll
;                 for (int n = 0; n < NT; ++n) Bf[n] = *(const LDSP bf16x8*)(sb + boff + n * (KS * 1024) + ks * 1024);
; #pragma unroll
;                 for (int m = 0; m < MT; ++m)
; #pragma unroll
;                     for (int n = 0; n < NT; ++n) acc[m][n] = __builtin_amdgcn_mfma_f32_16x16x32_bf16(Bf[n], At[m], acc[m][n], 0, 0, 0);
;             }
;             WAIT_V0(); __syncthreads();
;         }
	v_mfma_f32_16x16x32_bf16 v[52:55], v[88:91], v[72:75], v[52:55]
	s_mov_b32 m0, s38
	v_mfma_f32_16x16x32_bf16 v[60:63], v[92:95], v[72:75], v[60:63]
	v_mfma_f32_16x16x32_bf16 v[48:51], v[88:91], v[76:79], v[48:51]
	v_mfma_f32_16x16x32_bf16 v[64:67], v[92:95], v[76:79], v[64:67]
	v_mfma_f32_16x16x32_bf16 v[56:59], v[88:91], v[80:83], v[56:59]
	v_mfma_f32_16x16x32_bf16 v[68:71], v[92:95], v[80:83], v[68:71]
	v_mfma_f32_16x16x32_bf16 v[44:47], v[88:91], v[84:87], v[44:47]
	v_mfma_f32_16x16x32_bf16 v[40:43], v[92:95], v[84:87], v[40:43]
	ds_read_b128 v[72:75], v26 offset:1024
	ds_read_b128 v[76:79], v26 offset:5120
	ds_read_b128 v[80:83], v26 offset:9216
	ds_read_b128 v[84:87], v26 offset:13312
	ds_read_b128 v[88:91], v29
	ds_read_b128 v[92:95], v30
	s_waitcnt lgkmcnt(0)
	v_mfma_f32_16x16x32_bf16 v[52:55], v[88:91], v[72:75], v[52:55]
	v_mfma_f32_16x16x32_bf16 v[60:63], v[92:95], v[72:75], v[60:63]
	v_mfma_f32_16x16x32_bf16 v[48:51], v[88:91], v[76:79], v[48:51]
	v_mfma_f32_16x16x32_bf16 v[64:67], v[92:95], v[76:79], v[64:67]
	v_mfma_f32_16x16x32_bf16 v[56:59], v[88:91], v[80:83], v[56:59]
	v_mfma_f32_16x16x32_bf16 v[68:71], v[92:95], v[80:83], v[68:71]
	v_mfma_f32_16x16x32_bf16 v[44:47], v[88:91], v[84:87], v[44:47]
	v_mfma_f32_16x16x32_bf16 v[40:43], v[92:95], v[84:87], v[40:43]
	ds_read_b128 v[72:75], v26 offset:2048
	ds_read_b128 v[76:79], v26 offset:6144
	ds_read_b128 v[80:83], v26 offset:10240
	ds_read_b128 v[84:87], v26 offset:14336
	ds_read_b128 v[88:91], v31
	ds_read_b128 v[92:95], v36
	s_waitcnt lgkmcnt(0)
	v_mfma_f32_16x16x32_bf16 v[52:55], v[88:91], v[72:75], v[52:55]
	v_mfma_f32_16x16x32_bf16 v[60:63], v[92:95], v[72:75], v[60:63]
	v_mfma_f32_16x16x32_bf16 v[48:51], v[88:91], v[76:79], v[48:51]
	v_mfma_f32_16x16x32_bf16 v[64:67], v[92:95], v[76:79], v[64:67]
	v_mfma_f32_16x16x32_bf16 v[56:59], v[88:91], v[80:83], v[56:59]
	v_mfma_f32_16x16x32_bf16 v[68:71], v[92:95], v[80:83], v[68:71]
	v_mfma_f32_16x16x32_bf16 v[44:47], v[88:91], v[84:87], v[44:47]
	v_mfma_f32_16x16x32_bf16 v[40:43], v[92:95], v[84:87], v[40:43]
	ds_read_b128 v[72:75], v26 offset:3072
	ds_read_b128 v[76:79], v26 offset:7168
	ds_read_b128 v[80:83], v26 offset:11264
	ds_read_b128 v[84:87], v26 offset:15360
	ds_read_b128 v[88:91], v37
	ds_read_b128 v[92:95], v38
	s_waitcnt vmcnt(0)
	s_waitcnt vmcnt(0) lgkmcnt(0)
	v_mfma_f32_16x16x32_bf16 v[52:55], v[88:91], v[72:75], v[52:55]
	s_barrier
	v_mfma_f32_16x16x32_bf16 v[60:63], v[92:95], v[72:75], v[60:63]
	v_lshl_add_u64 v[72:73], v[2:3], 0, s[24:25]
	global_load_lds_dwordx4 v[72:73], off
	v_lshl_add_u64 v[72:73], v[0:1], 0, s[24:25]
	s_mov_b32 m0, s41
	v_mfma_f32_16x16x32_bf16 v[48:51], v[88:91], v[76:79], v[48:51]
	global_load_lds_dwordx4 v[72:73], off
	v_lshl_add_u64 v[72:73], v[6:7], 0, s[24:25]
	s_mov_b32 m0, s50
	v_mfma_f32_16x16x32_bf16 v[64:67], v[92:95], v[76:79], v[64:67]
	global_load_lds_dwordx4 v[72:73], off
	v_lshl_add_u64 v[72:73], v[4:5], 0, s[24:25]
	s_mov_b32 m0, s47
	v_mfma_f32_16x16x32_bf16 v[56:59], v[88:91], v[80:83], v[56:59]
	global_load_lds_dwordx4 v[72:73], off
	v_lshl_add_u64 v[72:73], v[10:11], 0, s[24:25]
	s_mov_b32 m0, s51
	v_mfma_f32_16x16x32_bf16 v[68:71], v[92:95], v[80:83], v[68:71]
	global_load_lds_dwordx4 v[72:73], off
	v_lshl_add_u64 v[72:73], v[8:9], 0, s[24:25]
	s_mov_b32 m0, s85
	v_mfma_f32_16x16x32_bf16 v[44:47], v[88:91], v[84:87], v[44:47]
	global_load_lds_dwordx4 v[72:73], off
	v_lshl_add_u64 v[72:73], v[14:15], 0, s[24:25]
	s_mov_b32 m0, s84
	v_mfma_f32_16x16x32_bf16 v[40:43], v[92:95], v[84:87], v[40:43]
	global_load_lds_dwordx4 v[72:73], off
	v_lshl_add_u64 v[72:73], v[12:13], 0, s[24:25]
	s_mov_b32 m0, s39
	s_nop 0
	global_load_lds_dwordx4 v[72:73], off
	ds_read_b128 v[72:75], v16
	ds_read_b128 v[76:79], v16 offset:4096
	ds_read_b128 v[80:83], v16 offset:8192
	ds_read_b128 v[84:87], v16 offset:12288
	ds_read_b128 v[88:91], v17 offset:32768
	ds_read_b128 v[92:95], v17 offset:36864
	s_waitcnt lgkmcnt(0)
	v_mfma_f32_16x16x32_bf16 v[52:55], v[88:91], v[72:75], v[52:55]
	s_mov_b32 m0, s11
	s_lshl_b32 s11, s34, 7
	s_addk_i32 s11, 0x4000
	v_mfma_f32_16x16x32_bf16 v[60:63], v[92:95], v[72:75], v[60:63]
	v_mfma_f32_16x16x32_bf16 v[48:51], v[88:91], v[76:79], v[48:51]
	v_mfma_f32_16x16x32_bf16 v[64:67], v[92:95], v[76:79], v[64:67]
	v_mfma_f32_16x16x32_bf16 v[56:59], v[88:91], v[80:83], v[56:59]
	v_mfma_f32_16x16x32_bf16 v[68:71], v[92:95], v[80:83], v[68:71]
	v_mfma_f32_16x16x32_bf16 v[44:47], v[88:91], v[84:87], v[44:47]
	v_mfma_f32_16x16x32_bf16 v[40:43], v[92:95], v[84:87], v[40:43]
	ds_read_b128 v[72:75], v16 offset:1024
	ds_read_b128 v[76:79], v16 offset:5120
	ds_read_b128 v[80:83], v16 offset:9216
	ds_read_b128 v[84:87], v16 offset:13312
	ds_read_b128 v[88:91], v17 offset:33792
	ds_read_b128 v[92:95], v17 offset:37888
	s_waitcnt lgkmcnt(0)
	v_mfma_f32_16x16x32_bf16 v[52:55], v[88:91], v[72:75], v[52:55]
	v_mfma_f32_16x16x32_bf16 v[60:63], v[92:95], v[72:75], v[60:63]
	v_mfma_f32_16x16x32_bf16 v[48:51], v[88:91], v[76:79], v[48:51]
	v_mfma_f32_16x16x32_bf16 v[64:67], v[92:95], v[76:79], v[64:67]
	v_mfma_f32_16x16x32_bf16 v[56:59], v[88:91], v[80:83], v[56:59]
	v_mfma_f32_16x16x32_bf16 v[68:71], v[92:95], v[80:83], v[68:71]
	v_mfma_f32_16x16x32_bf16 v[44:47], v[88:91], v[84:87], v[44:47]
	v_mfma_f32_16x16x32_bf16 v[40:43], v[92:95], v[84:87], v[40:43]
	ds_read_b128 v[72:75], v16 offset:2048
	ds_read_b128 v[76:79], v16 offset:6144
	ds_read_b128 v[80:83], v16 offset:10240
	ds_read_b128 v[84:87], v16 offset:14336
	ds_read_b128 v[88:91], v17 offset:34816
	ds_read_b128 v[92:95], v17 offset:38912
	s_waitcnt lgkmcnt(0)
	v_mfma_f32_16x16x32_bf16 v[52:55], v[88:91], v[72:75], v[52:55]
	v_mfma_f32_16x16x32_bf16 v[60:63], v[92:95], v[72:75], v[60:63]
	v_mfma_f32_16x16x32_bf16 v[48:51], v[88:91], v[76:79], v[48:51]
	v_mfma_f32_16x16x32_bf16 v[64:67], v[92:95], v[76:79], v[64:67]
	v_mfma_f32_16x16x32_bf16 v[56:59], v[88:91], v[80:83], v[56:59]
	v_mfma_f32_16x16x32_bf16 v[68:71], v[92:95], v[80:83], v[68:71]
	v_mfma_f32_16x16x32_bf16 v[44:47], v[88:91], v[84:87], v[44:47]
	v_mfma_f32_16x16x32_bf16 v[40:43], v[92:95], v[84:87], v[40:43]
	ds_read_b128 v[72:75], v16 offset:3072
	ds_read_b128 v[76:79], v16 offset:7168
	ds_read_b128 v[80:83], v16 offset:11264
	ds_read_b128 v[84:87], v16 offset:15360
	ds_read_b128 v[88:91], v17 offset:35840
	ds_read_b128 v[92:95], v17 offset:39936
	s_waitcnt vmcnt(0)
	s_waitcnt vmcnt(0) lgkmcnt(0)
	v_mfma_f32_16x16x32_bf16 v[52:55], v[88:91], v[72:75], v[52:55]
	s_barrier
; #define LDSP __attribute__((address_space(3)))
; #define WAIT_V0() asm volatile("s_waitcnt vmcnt(0)" ::: "memory")
; template <int EK, int TS, int KS>
; DI void ctx_tiles(const Params& p, int l, const bf16_t* __restrict__ A, const bf16_t* __restrict__ Bt, int N, int K, ldsp_t shm) {
;     ...
;         for (int t = 0; t < nt; ++t) {
;             const int cur = t & 1;
;             if (t + 1 < nt) C_STAGE(cur ^ 1, t + 1);
;             ldsp_t sa = shm + cur * 2 * TILE_A, sb = sa + TILE_A;
; #pragma unroll
;             for (int ks = 0; ks < KS; ++ks) {
;                 bf16x8 At[MT], Bf[NT];
; #pragma unroll
;                 for (int m = 0; m < MT; ++m) At[m] = *(const LDSP bf16x8*)(sa + aoff + m * (KS * 1024) + ks * 1024);
; #pragma unroll
;                 for (int n = 0; n < NT; ++n) Bf[n] = *(const LDSP bf16x8*)(sb + boff + n * (KS * 1024) + ks * 1024);
; #pragma unroll
;                 for (int m = 0; m < MT; ++m)
; #pragma unroll
;                     for (int n = 0; n < NT; ++n) acc[m][n] = __builtin_amdgcn_mfma_f32_16x16x32_bf16(Bf[n], At[m], acc[m][n], 0, 0, 0);
;             }
;             WAIT_V0(); __syncthreads();
;         }
	v_mfma_f32_16x16x32_bf16 v[60:63], v[92:95], v[72:75], v[60:63]
	v_lshl_add_u64 v[72:73], v[2:3], 0, s[16:17]
	global_load_lds_dwordx4 v[72:73], off
	v_lshl_add_u64 v[72:73], v[0:1], 0, s[16:17]
	s_mov_b32 m0, s10
	v_mfma_f32_16x16x32_bf16 v[48:51], v[88:91], v[76:79], v[48:51]
	global_load_lds_dwordx4 v[72:73], off
	v_lshl_add_u64 v[72:73], v[6:7], 0, s[16:17]
	s_mov_b32 m0, s37
	v_mfma_f32_16x16x32_bf16 v[64:67], v[92:95], v[76:79], v[64:67]
	global_load_lds_dwordx4 v[72:73], off
	v_lshl_add_u64 v[72:73], v[4:5], 0, s[16:17]
	s_mov_b32 m0, s35
	v_mfma_f32_16x16x32_bf16 v[56:59], v[88:91], v[80:83], v[56:59]
	global_load_lds_dwordx4 v[72:73], off
	v_lshl_add_u64 v[72:73], v[10:11], 0, s[16:17]
	s_mov_b32 m0, s43
	v_mfma_f32_16x16x32_bf16 v[68:71], v[92:95], v[80:83], v[68:71]
	global_load_lds_dwordx4 v[72:73], off
	v_lshl_add_u64 v[72:73], v[8:9], 0, s[16:17]
	s_mov_b32 m0, s42
	v_mfma_f32_16x16x32_bf16 v[44:47], v[88:91], v[84:87], v[44:47]
	global_load_lds_dwordx4 v[72:73], off
	v_lshl_add_u64 v[72:73], v[14:15], 0, s[16:17]
	s_mov_b32 m0, s46
	v_mfma_f32_16x16x32_bf16 v[40:43], v[92:95], v[84:87], v[40:43]
	global_load_lds_dwordx4 v[72:73], off
	v_lshl_add_u64 v[72:73], v[12:13], 0, s[16:17]
	s_mov_b32 m0, s40
	v_readfirstlane_b32 s10, v18
	global_load_lds_dwordx4 v[72:73], off
	ds_read_b128 v[72:75], v26
	ds_read_b128 v[76:79], v26 offset:4096
	ds_read_b128 v[80:83], v26 offset:8192
	ds_read_b128 v[84:87], v26 offset:12288
	ds_read_b128 v[88:91], v27
	ds_read_b128 v[92:95], v28
	s_waitcnt lgkmcnt(0)
	v_mfma_f32_16x16x32_bf16 v[52:55], v[88:91], v[72:75], v[52:55]
	v_lshl_add_u64 v[2:3], v[2:3], 0, s[26:27]
	s_mov_b32 m0, s10
	v_readfirstlane_b32 s10, v19
	v_mfma_f32_16x16x32_bf16 v[60:63], v[92:95], v[72:75], v[60:63]
	v_lshl_add_u64 v[0:1], v[0:1], 0, s[26:27]
	v_mfma_f32_16x16x32_bf16 v[48:51], v[88:91], v[76:79], v[48:51]
	v_mfma_f32_16x16x32_bf16 v[64:67], v[92:95], v[76:79], v[64:67]
	v_mfma_f32_16x16x32_bf16 v[56:59], v[88:91], v[80:83], v[56:59]
	v_mfma_f32_16x16x32_bf16 v[68:71], v[92:95], v[80:83], v[68:71]
	v_mfma_f32_16x16x32_bf16 v[44:47], v[88:91], v[84:87], v[44:47]
	v_mfma_f32_16x16x32_bf16 v[40:43], v[92:95], v[84:87], v[40:43]
	ds_read_b128 v[72:75], v26 offset:1024
	ds_read_b128 v[76:79], v26 offset:5120
	ds_read_b128 v[80:83], v26 offset:9216
	ds_read_b128 v[84:87], v26 offset:13312
	ds_read_b128 v[88:91], v29
	ds_read_b128 v[92:95], v30
	s_waitcnt lgkmcnt(0)
	v_mfma_f32_16x16x32_bf16 v[52:55], v[88:91], v[72:75], v[52:55]
	v_mfma_f32_16x16x32_bf16 v[60:63], v[92:95], v[72:75], v[60:63]
	v_mfma_f32_16x16x32_bf16 v[48:51], v[88:91], v[76:79], v[48:51]
	v_mfma_f32_16x16x32_bf16 v[64:67], v[92:95], v[76:79], v[64:67]
	v_mfma_f32_16x16x32_bf16 v[56:59], v[88:91], v[80:83], v[56:59]
	v_mfma_f32_16x16x32_bf16 v[68:71], v[92:95], v[80:83], v[68:71]
	v_mfma_f32_16x16x32_bf16 v[44:47], v[88:91], v[84:87], v[44:47]
	v_mfma_f32_16x16x32_bf16 v[40:43], v[92:95], v[84:87], v[40:43]
	ds_read_b128 v[72:75], v26 offset:2048
	ds_read_b128 v[76:79], v26 offset:6144
	ds_read_b128 v[80:83], v26 offset:10240
	ds_read_b128 v[84:87], v26 offset:14336
	ds_read_b128 v[88:91], v31
	ds_read_b128 v[92:95], v36
	s_waitcnt lgkmcnt(0)
	v_mfma_f32_16x16x32_bf16 v[52:55], v[88:91], v[72:75], v[52:55]
	v_mfma_f32_16x16x32_bf16 v[60:63], v[92:95], v[72:75], v[60:63]
	v_mfma_f32_16x16x32_bf16 v[48:51], v[88:91], v[76:79], v[48:51]
	v_mfma_f32_16x16x32_bf16 v[64:67], v[92:95], v[76:79], v[64:67]
	v_mfma_f32_16x16x32_bf16 v[56:59], v[88:91], v[80:83], v[56:59]
	v_mfma_f32_16x16x32_bf16 v[68:71], v[92:95], v[80:83], v[68:71]
	v_mfma_f32_16x16x32_bf16 v[44:47], v[88:91], v[84:87], v[44:47]
	v_mfma_f32_16x16x32_bf16 v[40:43], v[92:95], v[84:87], v[40:43]
	ds_read_b128 v[72:75], v26 offset:3072
	ds_read_b128 v[76:79], v26 offset:7168
	ds_read_b128 v[80:83], v26 offset:11264
	ds_read_b128 v[84:87], v26 offset:15360
	ds_read_b128 v[88:91], v37
	ds_read_b128 v[92:95], v38
	s_waitcnt vmcnt(0)
	s_waitcnt vmcnt(0) lgkmcnt(0)
	s_barrier
	global_load_lds_dwordx4 v[2:3], off
	s_mov_b32 m0, s10
	v_readfirstlane_b32 s10, v20
	global_load_lds_dwordx4 v[0:1], off
	v_lshl_add_u64 v[0:1], v[6:7], 0, s[26:27]
	s_mov_b32 m0, s10
	v_readfirstlane_b32 s10, v21
	global_load_lds_dwordx4 v[0:1], off
	v_lshl_add_u64 v[0:1], v[4:5], 0, s[26:27]
	s_mov_b32 m0, s10
	v_readfirstlane_b32 s10, v22
	global_load_lds_dwordx4 v[0:1], off
	v_lshl_add_u64 v[0:1], v[10:11], 0, s[26:27]
	s_mov_b32 m0, s10
	v_readfirstlane_b32 s10, v23
	global_load_lds_dwordx4 v[0:1], off
	v_lshl_add_u64 v[0:1], v[8:9], 0, s[26:27]
	s_mov_b32 m0, s10
	v_readfirstlane_b32 s10, v24
	global_load_lds_dwordx4 v[0:1], off
	v_lshl_add_u64 v[0:1], v[14:15], 0, s[26:27]
	s_mov_b32 m0, s10
	v_readfirstlane_b32 s10, v25
	global_load_lds_dwordx4 v[0:1], off
	v_lshl_add_u64 v[0:1], v[12:13], 0, s[26:27]
	s_mov_b32 m0, s10
	v_mfma_f32_16x16x32_bf16 v[52:55], v[88:91], v[72:75], v[52:55]
	global_load_lds_dwordx4 v[0:1], off
	ds_read_b128 v[0:3], v16
	ds_read_b128 v[4:7], v16 offset:4096
	ds_read_b128 v[8:11], v16 offset:8192
	ds_read_b128 v[12:15], v16 offset:12288
	ds_read_b128 v[18:21], v17 offset:32768
	ds_read_b128 v[22:25], v17 offset:36864
	v_mfma_f32_16x16x32_bf16 v[60:63], v[92:95], v[72:75], v[60:63]
	s_lshl_b32 s10, s36, 7
	v_mfma_f32_16x16x32_bf16 v[48:51], v[88:91], v[76:79], v[48:51]
	v_mfma_f32_16x16x32_bf16 v[64:67], v[92:95], v[76:79], v[64:67]
	v_mfma_f32_16x16x32_bf16 v[56:59], v[88:91], v[80:83], v[56:59]
	v_mfma_f32_16x16x32_bf16 v[68:71], v[92:95], v[80:83], v[68:71]
	v_mfma_f32_16x16x32_bf16 v[44:47], v[88:91], v[84:87], v[44:47]
	v_mfma_f32_16x16x32_bf16 v[40:43], v[92:95], v[84:87], v[40:43]
	s_waitcnt lgkmcnt(0)
; #define LDSP __attribute__((address_space(3)))
; #define WAIT_V0() asm volatile("s_waitcnt vmcnt(0)" ::: "memory")
; template <int EK, int TS, int KS>
; DI void ctx_tiles(const Params& p, int l, const bf16_t* __restrict__ A, const bf16_t* __restrict__ Bt, int N, int K, ldsp_t shm) {
;     ...
;         for (int t = 0; t < nt; ++t) {
;             const int cur = t & 1;
;             if (t + 1 < nt) C_STAGE(cur ^ 1, t + 1);
;             ldsp_t sa = shm + cur * 2 * TILE_A, sb = sa + TILE_A;
; #pragma unroll
;             for (int ks = 0; ks < KS; ++ks) {
;                 bf16x8 At[MT], Bf[NT];
; #pragma unroll
;                 for (int m = 0; m < MT; ++m) At[m] = *(const LDSP bf16x8*)(sa + aoff + m * (KS * 1024) + ks * 1024);
; #pragma unroll
;                 for (int n = 0; n < NT; ++n) Bf[n] = *(const LDSP bf16x8*)(sb + boff + n * (KS * 1024) + ks * 1024);
; #pragma unroll
;                 for (int m = 0; m < MT; ++m)
; #pragma unroll
;                     for (int n = 0; n < NT; ++n) acc[m][n] = __builtin_amdgcn_mfma_f32_16x16x32_bf16(Bf[n], At[m], acc[m][n], 0, 0, 0);
;             }
;             WAIT_V0(); __syncthreads();
;         }
	v_mfma_f32_16x16x32_bf16 v[52:55], v[18:21], v[0:3], v[52:55]
	v_mfma_f32_16x16x32_bf16 v[0:3], v[22:25], v[0:3], v[60:63]
	v_mfma_f32_16x16x32_bf16 v[48:51], v[18:21], v[4:7], v[48:51]
	v_mfma_f32_16x16x32_bf16 v[4:7], v[22:25], v[4:7], v[64:67]
	v_mfma_f32_16x16x32_bf16 v[56:59], v[18:21], v[8:11], v[56:59]
	v_mfma_f32_16x16x32_bf16 v[8:11], v[22:25], v[8:11], v[68:71]
	v_mfma_f32_16x16x32_bf16 v[18:21], v[18:21], v[12:15], v[44:47]
	v_mfma_f32_16x16x32_bf16 v[12:15], v[22:25], v[12:15], v[40:43]
	ds_read_b128 v[22:25], v16 offset:1024
	s_nop 1
	ds_read_b128 v[40:43], v16 offset:5120
	ds_read_b128 v[44:47], v16 offset:9216
	ds_read_b128 v[60:63], v16 offset:13312
	ds_read_b128 v[64:67], v17 offset:33792
	ds_read_b128 v[68:71], v17 offset:37888
	s_waitcnt lgkmcnt(0)
	v_mfma_f32_16x16x32_bf16 v[52:55], v[64:67], v[22:25], v[52:55]
	v_mfma_f32_16x16x32_bf16 v[0:3], v[68:71], v[22:25], v[0:3]
	v_mfma_f32_16x16x32_bf16 v[22:25], v[64:67], v[40:43], v[48:51]
	v_mfma_f32_16x16x32_bf16 v[4:7], v[68:71], v[40:43], v[4:7]
	v_mfma_f32_16x16x32_bf16 v[40:43], v[64:67], v[44:47], v[56:59]
	v_mfma_f32_16x16x32_bf16 v[8:11], v[68:71], v[44:47], v[8:11]
	v_mfma_f32_16x16x32_bf16 v[18:21], v[64:67], v[60:63], v[18:21]
	v_mfma_f32_16x16x32_bf16 v[12:15], v[68:71], v[60:63], v[12:15]
	ds_read_b128 v[44:47], v16 offset:2048
	ds_read_b128 v[48:51], v16 offset:6144
	ds_read_b128 v[56:59], v16 offset:10240
	ds_read_b128 v[60:63], v16 offset:14336
	ds_read_b128 v[64:67], v17 offset:34816
	ds_read_b128 v[68:71], v17 offset:38912
	s_waitcnt lgkmcnt(0)
	v_mfma_f32_16x16x32_bf16 v[52:55], v[64:67], v[44:47], v[52:55]
	v_mfma_f32_16x16x32_bf16 v[0:3], v[68:71], v[44:47], v[0:3]
	v_mfma_f32_16x16x32_bf16 v[22:25], v[64:67], v[48:51], v[22:25]
	v_mfma_f32_16x16x32_bf16 v[4:7], v[68:71], v[48:51], v[4:7]
	v_mfma_f32_16x16x32_bf16 v[40:43], v[64:67], v[56:59], v[40:43]
	v_mfma_f32_16x16x32_bf16 v[8:11], v[68:71], v[56:59], v[8:11]
	v_mfma_f32_16x16x32_bf16 v[18:21], v[64:67], v[60:63], v[18:21]
	v_mfma_f32_16x16x32_bf16 v[12:15], v[68:71], v[60:63], v[12:15]
	ds_read_b128 v[44:47], v16 offset:3072
	ds_read_b128 v[48:51], v16 offset:7168
	ds_read_b128 v[56:59], v16 offset:11264
	ds_read_b128 v[60:63], v16 offset:15360
	ds_read_b128 v[64:67], v17 offset:35840
	ds_read_b128 v[68:71], v17 offset:39936
	s_waitcnt vmcnt(0)
	s_waitcnt vmcnt(0) lgkmcnt(0)
	v_mfma_f32_16x16x32_bf16 v[52:55], v[64:67], v[44:47], v[52:55]
	s_barrier
	v_mfma_f32_16x16x32_bf16 v[0:3], v[68:71], v[44:47], v[0:3]
	v_mfma_f32_16x16x32_bf16 v[22:25], v[64:67], v[48:51], v[22:25]
	v_mfma_f32_16x16x32_bf16 v[4:7], v[68:71], v[48:51], v[4:7]
	v_mfma_f32_16x16x32_bf16 v[40:43], v[64:67], v[56:59], v[40:43]
	v_mfma_f32_16x16x32_bf16 v[8:11], v[68:71], v[56:59], v[8:11]
	v_mfma_f32_16x16x32_bf16 v[16:19], v[64:67], v[60:63], v[18:21]
	v_mfma_f32_16x16x32_bf16 v[12:15], v[68:71], v[60:63], v[12:15]
	ds_read_b128 v[44:47], v28
	ds_read_b128 v[48:51], v27
	ds_read_b128 v[56:59], v26 offset:12288
	ds_read_b128 v[60:63], v26 offset:8192
	ds_read_b128 v[64:67], v26 offset:4096
	ds_read_b128 v[68:71], v26
	s_waitcnt lgkmcnt(0)
	v_mfma_f32_16x16x32_bf16 v[52:55], v[48:51], v[68:71], v[52:55]
	v_mfma_f32_16x16x32_bf16 v[0:3], v[44:47], v[68:71], v[0:3]
	v_mfma_f32_16x16x32_bf16 v[20:23], v[48:51], v[64:67], v[22:25]
	v_mfma_f32_16x16x32_bf16 v[4:7], v[44:47], v[64:67], v[4:7]
	v_mfma_f32_16x16x32_bf16 v[40:43], v[48:51], v[60:63], v[40:43]
	v_mfma_f32_16x16x32_bf16 v[8:11], v[44:47], v[60:63], v[8:11]
	v_mfma_f32_16x16x32_bf16 v[16:19], v[48:51], v[56:59], v[16:19]
	v_mfma_f32_16x16x32_bf16 v[12:15], v[44:47], v[56:59], v[12:15]
	ds_read_b128 v[44:47], v26 offset:1024
	ds_read_b128 v[48:51], v26 offset:5120
	ds_read_b128 v[56:59], v26 offset:9216
	ds_read_b128 v[60:63], v26 offset:13312
	ds_read_b128 v[64:67], v29
	ds_read_b128 v[68:71], v30
	s_waitcnt lgkmcnt(1)
	v_mfma_f32_16x16x32_bf16 v[52:55], v[64:67], v[44:47], v[52:55]
	s_waitcnt lgkmcnt(0)
	v_mfma_f32_16x16x32_bf16 v[0:3], v[68:71], v[44:47], v[0:3]
	v_mfma_f32_16x16x32_bf16 v[20:23], v[64:67], v[48:51], v[20:23]
	v_mfma_f32_16x16x32_bf16 v[4:7], v[68:71], v[48:51], v[4:7]
	v_mfma_f32_16x16x32_bf16 v[40:43], v[64:67], v[56:59], v[40:43]
	v_mfma_f32_16x16x32_bf16 v[8:11], v[68:71], v[56:59], v[8:11]
	v_mfma_f32_16x16x32_bf16 v[16:19], v[64:67], v[60:63], v[16:19]
	v_mfma_f32_16x16x32_bf16 v[12:15], v[68:71], v[60:63], v[12:15]
	ds_read_b128 v[44:47], v26 offset:2048
	ds_read_b128 v[48:51], v26 offset:6144
	ds_read_b128 v[56:59], v26 offset:10240
	ds_read_b128 v[60:63], v26 offset:14336
	ds_read_b128 v[28:31], v31
	ds_read_b128 v[64:67], v36
	s_waitcnt lgkmcnt(1)
	v_mfma_f32_16x16x32_bf16 v[52:55], v[28:31], v[44:47], v[52:55]
	s_waitcnt lgkmcnt(0)
	v_mfma_f32_16x16x32_bf16 v[0:3], v[64:67], v[44:47], v[0:3]
	v_mfma_f32_16x16x32_bf16 v[20:23], v[28:31], v[48:51], v[20:23]
	v_mfma_f32_16x16x32_bf16 v[44:47], v[64:67], v[48:51], v[4:7]
	v_mfma_f32_16x16x32_bf16 v[40:43], v[28:31], v[56:59], v[40:43]
	v_mfma_f32_16x16x32_bf16 v[48:51], v[64:67], v[56:59], v[8:11]
	v_mfma_f32_16x16x32_bf16 v[56:59], v[28:31], v[60:63], v[16:19]
	v_mfma_f32_16x16x32_bf16 v[60:63], v[64:67], v[60:63], v[12:15]
	ds_read_b128 v[4:7], v26 offset:3072
	ds_read_b128 v[8:11], v26 offset:7168
	ds_read_b128 v[16:19], v26 offset:11264
	ds_read_b128 v[24:27], v26 offset:15360
	ds_read_b128 v[64:67], v37
	ds_read_b128 v[36:39], v38
	s_waitcnt vmcnt(0)
	s_waitcnt lgkmcnt(0)
	v_mfma_f32_16x16x32_bf16 v[28:31], v[64:67], v[4:7], v[52:55]
	s_barrier
; #define LDSP __attribute__((address_space(3)))
; DI unsigned pk2(float a, float b) { f32x2 v = {a, b}; bf2_t r = __builtin_convertvector(v, bf2_t); return __builtin_bit_cast(unsigned, r); }
; template <int EK>
; DI void ctx_item(const Params& p, int l, int grow, int gcol, int slot, f32x4 s0, f32x4 s1, bool lead) {
;     ...
;         const float* pp = p.ss + ((size_t)(l * 2 + 1) * NTOK + NLAT + grow) * 16;
;         const f32x4 q0 = *(const f32x4*)pp, q1 = *(const f32x4*)(pp + 4), q2 = *(const f32x4*)(pp + 8), q3 = *(const f32x4*)(pp + 12);
;         const f32x4 qs = q0 + q1 + q2 + q3;
;         const float rstd = rsqrtf((qs[0] + qs[1] + qs[2] + qs[3]) * (1.f / DM) + EPS);
;         const float* shw = p.shw_ff1 + ((size_t)l * 5 + 4) * FF + gcol;
;         const f32x4 h0 = *(const f32x4*)shw, h1 = *(const f32x4*)(shw + 4);
;         s0 = s0 * rstd + h0; s1 = s1 * rstd + h1;
; #pragma unroll
;         for (int j = 0; j < 4; ++j) { float r0 = fmaxf(s0[j], 0.f), r1 = fmaxf(s1[j], 0.f); s0[j] = r0 * r0; s1[j] = r1 * r1; }
;         u32x4 w; w[0] = pk2(s0[0], s0[1]); w[1] = pk2(s0[2], s0[3]); w[2] = pk2(s1[0], s1[1]); w[3] = pk2(s1[2], s1[3]);
;         *(u32x4*)(p.ACT + (size_t)(NLAT + grow) * FF + gcol) = w;
; template <int EK, int TS, int KS>
; DI void ctx_tiles(const Params& p, int l, const bf16_t* __restrict__ A, const bf16_t* __restrict__ Bt, int N, int K, ldsp_t shm) {
;     ...
; #pragma unroll
;         for (int m = 0; m < MT; ++m)
; #pragma unroll
;             for (int n = 0; n < NT; ++n) {
;                 const int row = wr * WM + m * 16 + fr, ch = (wc * WN + n * 16 + fq * 4) >> 2;
;                 *(LDSP f32x4*)(shm + row * (TS * 4) + ((ch ^ (row & 15)) << 4)) = acc[m][n];
;             }
;         __syncthreads();
; #pragma unroll
;         for (int it = 0; it < (TS * TS / 8) / 512; ++it) {
;             const int item = it * 512 + tid, row = item / (TS / 8), c8 = item % (TS / 8);
;             const f32x4 s0 = *(const LDSP f32x4*)(shm + row * (TS * 4) + (((2 * c8) ^ (row & 15)) << 4));
;             const f32x4 s1 = *(const LDSP f32x4*)(shm + row * (TS * 4) + (((2 * c8 + 1) ^ (row & 15)) << 4));
;             ctx_item<EK>(p, l, tm * TS + row, tn * TS + c8 * 8, tn, s0, s1, c8 == 0);
	v_mfma_f32_16x16x32_bf16 v[0:3], v[36:39], v[4:7], v[0:3]
	v_mfma_f32_16x16x32_bf16 v[4:7], v[64:67], v[8:11], v[20:23]
	v_mfma_f32_16x16x32_bf16 v[8:11], v[36:39], v[8:11], v[44:47]
	v_mfma_f32_16x16x32_bf16 v[12:15], v[64:67], v[16:19], v[40:43]
	v_mfma_f32_16x16x32_bf16 v[16:19], v[36:39], v[16:19], v[48:51]
	v_mfma_f32_16x16x32_bf16 v[20:23], v[64:67], v[24:27], v[56:59]
	v_mfma_f32_16x16x32_bf16 v[24:27], v[36:39], v[24:27], v[60:63]
	v_lshrrev_b32_e32 v36, 2, v32
	v_and_or_b32 v35, v36, 12, v35
	v_lshrrev_b32_e32 v35, 2, v35
	v_bitop3_b32 v36, v35, v32, 15 bitop3:0x78
	v_lshl_or_b32 v36, v36, 4, v34
	ds_write_b128 v36, v[28:31]
	v_bitop3_b32 v28, v35, v33, 4 bitop3:0x36
	v_lshl_or_b32 v28, v28, 4, v34
	ds_write_b128 v28, v[0:3]
	ds_write_b128 v36, v[4:7] offset:8192
	ds_write_b128 v28, v[8:11] offset:8192
	ds_write_b128 v36, v[12:15] offset:16384
	ds_write_b128 v28, v[16:19] offset:16384
	ds_write_b128 v36, v[20:23] offset:24576
	ds_write_b128 v28, v[24:27] offset:24576
	v_ashrrev_i32_e32 v0, 31, v32
	v_lshrrev_b32_e32 v0, 28, v0
	v_add_u32_e32 v0, v32, v0
	v_ashrrev_i32_e32 v8, 4, v0
	v_and_b32_e32 v0, -16, v0
	v_sub_u32_e32 v9, v32, v0
	v_add_u32_e32 v26, s11, v8
	v_lshlrev_b32_e32 v5, 1, v9
	v_ashrrev_i32_e32 v27, 31, v26
	v_lshlrev_b32_e32 v4, 9, v8
	v_and_b32_e32 v6, 15, v8
	v_bitop3_b32 v0, v5, v8, 15 bitop3:0x78
	v_lshl_add_u32 v24, v9, 3, s10
	v_lshl_add_u64 v[8:9], s[4:5], 0, v[26:27]
	v_bitop3_b32 v5, v5, v6, 1 bitop3:0x36
	v_lshlrev_b64 v[8:9], 6, v[8:9]
	v_lshl_add_u32 v0, v0, 4, v4
	v_lshl_add_u32 v4, v5, 4, v4
	v_lshl_add_u64 v[20:21], s[74:75], 0, v[8:9]
	s_waitcnt lgkmcnt(0)
	s_barrier
	ds_read_b128 v[0:3], v0
	ds_read_b128 v[4:7], v4
	global_load_dwordx4 v[8:11], v[20:21], off offset:48
	global_load_dwordx4 v[12:15], v[20:21], off offset:32
	global_load_dwordx4 v[16:19], v[20:21], off
	s_nop 0
	global_load_dwordx4 v[20:23], v[20:21], off offset:16
	v_ashrrev_i32_e32 v25, 31, v24
	s_waitcnt vmcnt(0)
	v_pk_add_f32 v[16:17], v[16:17], v[20:21]
	v_pk_add_f32 v[18:19], v[18:19], v[22:23]
	v_pk_add_f32 v[12:13], v[16:17], v[12:13]
	v_pk_add_f32 v[14:15], v[18:19], v[14:15]
	v_pk_add_f32 v[8:9], v[12:13], v[8:9]
	v_pk_add_f32 v[10:11], v[14:15], v[10:11]
	v_add_f32_e32 v8, v8, v9
	v_add_f32_e32 v8, v10, v8
	v_add_f32_e32 v8, v11, v8
	v_fmamk_f32 v8, v8, 0x3a800000, v208
	v_cmp_gt_f32_e32 vcc, s92, v8
	v_mul_f32_e32 v9, 0x4b800000, v8
	v_lshl_add_u64 v[12:13], v[24:25], 2, s[6:7]
	v_cndmask_b32_e32 v8, v8, v9, vcc
	v_rsq_f32_e32 v8, v8
	s_nop 0
	v_mul_f32_e32 v9, 0x45800000, v8
	v_cndmask_b32_e32 v16, v8, v9, vcc
	global_load_dwordx4 v[8:11], v[12:13], off offset:16
	s_nop 0
	global_load_dwordx4 v[12:15], v[12:13], off
	s_waitcnt vmcnt(1) lgkmcnt(0)
	v_pk_fma_f32 v[4:5], v[4:5], v[16:17], v[8:9] op_sel_hi:[1,0,1]
	s_waitcnt vmcnt(0)
	v_pk_fma_f32 v[2:3], v[2:3], v[16:17], v[14:15] op_sel_hi:[1,0,1]
	v_pk_fma_f32 v[0:1], v[0:1], v[16:17], v[12:13] op_sel_hi:[1,0,1]
	v_max_f32_e32 v4, 0, v4
	v_max_f32_e32 v0, 0, v0
	v_max_f32_e32 v1, 0, v1
	v_max_f32_e32 v5, 0, v5
	v_max_f32_e32 v2, 0, v2
	v_max_f32_e32 v3, 0, v3
	v_pk_fma_f32 v[6:7], v[6:7], v[16:17], v[10:11] op_sel_hi:[1,0,1]
	v_pk_mul_f32 v[0:1], v[0:1], v[0:1]
	v_pk_mul_f32 v[4:5], v[4:5], v[4:5]
	v_pk_mul_f32 v[2:3], v[2:3], v[2:3]
	v_max_f32_e32 v6, 0, v6
	v_max_f32_e32 v7, 0, v7
	v_cvt_pk_bf16_f32 v0, v0, v1
	v_cvt_pk_bf16_f32 v1, v2, v3
	v_cvt_pk_bf16_f32 v2, v4, v5
	v_lshlrev_b64 v[4:5], 13, v[26:27]
	v_pk_mul_f32 v[6:7], v[6:7], v[6:7]
	v_lshl_add_u64 v[4:5], s[12:13], 0, v[4:5]
	v_cvt_pk_bf16_f32 v3, v6, v7
	v_lshl_add_u64 v[4:5], v[24:25], 1, v[4:5]
	global_store_dwordx4 v[4:5], v[0:3], off sc1
	s_nop 1
	v_add_u32_e32 v0, 0x200, v32
	v_ashrrev_i32_e32 v1, 31, v0
	v_lshrrev_b32_e32 v1, 28, v1
	v_add_u32_e32 v1, v0, v1
	v_ashrrev_i32_e32 v8, 4, v1
	v_and_b32_e32 v1, -16, v1
	v_sub_u32_e32 v9, v0, v1
	v_add_u32_e32 v26, s11, v8
	v_lshlrev_b32_e32 v5, 1, v9
	v_ashrrev_i32_e32 v27, 31, v26
	v_lshlrev_b32_e32 v4, 9, v8
	v_and_b32_e32 v6, 15, v8
	v_bitop3_b32 v0, v5, v8, 15 bitop3:0x78
	v_lshl_add_u32 v24, v9, 3, s10
	v_lshl_add_u64 v[8:9], s[4:5], 0, v[26:27]
	v_bitop3_b32 v5, v5, v6, 1 bitop3:0x36
	v_lshlrev_b64 v[8:9], 6, v[8:9]
	v_lshl_add_u32 v0, v0, 4, v4
	v_lshl_add_u32 v4, v5, 4, v4
	v_lshl_add_u64 v[20:21], s[74:75], 0, v[8:9]
	ds_read_b128 v[0:3], v0
	ds_read_b128 v[4:7], v4
	global_load_dwordx4 v[8:11], v[20:21], off offset:48
	global_load_dwordx4 v[12:15], v[20:21], off offset:32
	global_load_dwordx4 v[16:19], v[20:21], off
	s_nop 0
	global_load_dwordx4 v[20:23], v[20:21], off offset:16
	v_ashrrev_i32_e32 v25, 31, v24
	s_waitcnt vmcnt(0)
	v_pk_add_f32 v[16:17], v[16:17], v[20:21]
	v_pk_add_f32 v[18:19], v[18:19], v[22:23]
	v_pk_add_f32 v[12:13], v[16:17], v[12:13]
	v_pk_add_f32 v[14:15], v[18:19], v[14:15]
	v_pk_add_f32 v[8:9], v[12:13], v[8:9]
	v_pk_add_f32 v[10:11], v[14:15], v[10:11]
	v_add_f32_e32 v8, v8, v9
	v_add_f32_e32 v8, v10, v8
	v_add_f32_e32 v8, v11, v8
	v_fmamk_f32 v8, v8, 0x3a800000, v208
	v_cmp_gt_f32_e32 vcc, s92, v8
	v_mul_f32_e32 v9, 0x4b800000, v8
	v_lshl_add_u64 v[12:13], v[24:25], 2, s[6:7]
	v_cndmask_b32_e32 v8, v8, v9, vcc
	v_rsq_f32_e32 v8, v8
	s_nop 0
	v_mul_f32_e32 v9, 0x45800000, v8
	v_cndmask_b32_e32 v16, v8, v9, vcc
	global_load_dwordx4 v[8:11], v[12:13], off offset:16
	s_nop 0
	global_load_dwordx4 v[12:15], v[12:13], off
	s_waitcnt vmcnt(1) lgkmcnt(0)
	v_pk_fma_f32 v[4:5], v[4:5], v[16:17], v[8:9] op_sel_hi:[1,0,1]
	s_waitcnt vmcnt(0)
; #define LDSP __attribute__((address_space(3)))
; DI unsigned pk2(float a, float b) { f32x2 v = {a, b}; bf2_t r = __builtin_convertvector(v, bf2_t); return __builtin_bit_cast(unsigned, r); }
; template <int EK>
; DI void ctx_item(const Params& p, int l, int grow, int gcol, int slot, f32x4 s0, f32x4 s1, bool lead) {
;     ...
;         const float* pp = p.ss + ((size_t)(l * 2 + 1) * NTOK + NLAT + grow) * 16;
;         const f32x4 q0 = *(const f32x4*)pp, q1 = *(const f32x4*)(pp + 4), q2 = *(const f32x4*)(pp + 8), q3 = *(const f32x4*)(pp + 12);
;         const f32x4 qs = q0 + q1 + q2 + q3;
;         const float rstd = rsqrtf((qs[0] + qs[1] + qs[2] + qs[3]) * (1.f / DM) + EPS);
;         const float* shw = p.shw_ff1 + ((size_t)l * 5 + 4) * FF + gcol;
;         const f32x4 h0 = *(const f32x4*)shw, h1 = *(const f32x4*)(shw + 4);
;         s0 = s0 * rstd + h0; s1 = s1 * rstd + h1;
; #pragma unroll
;         for (int j = 0; j < 4; ++j) { float r0 = fmaxf(s0[j], 0.f), r1 = fmaxf(s1[j], 0.f); s0[j] = r0 * r0; s1[j] = r1 * r1; }
;         u32x4 w; w[0] = pk2(s0[0], s0[1]); w[1] = pk2(s0[2], s0[3]); w[2] = pk2(s1[0], s1[1]); w[3] = pk2(s1[2], s1[3]);
;         *(u32x4*)(p.ACT + (size_t)(NLAT + grow) * FF + gcol) = w;
; template <int EK, int TS, int KS>
; DI void ctx_tiles(const Params& p, int l, const bf16_t* __restrict__ A, const bf16_t* __restrict__ Bt, int N, int K, ldsp_t shm) {
;     ...
; #pragma unroll
;         for (int it = 0; it < (TS * TS / 8) / 512; ++it) {
;             const int item = it * 512 + tid, row = item / (TS / 8), c8 = item % (TS / 8);
;             const f32x4 s0 = *(const LDSP f32x4*)(shm + row * (TS * 4) + (((2 * c8) ^ (row & 15)) << 4));
;             const f32x4 s1 = *(const LDSP f32x4*)(shm + row * (TS * 4) + (((2 * c8 + 1) ^ (row & 15)) << 4));
;             ctx_item<EK>(p, l, tm * TS + row, tn * TS + c8 * 8, tn, s0, s1, c8 == 0);
;         }
;         __syncthreads();
	v_pk_fma_f32 v[2:3], v[2:3], v[16:17], v[14:15] op_sel_hi:[1,0,1]
	v_pk_fma_f32 v[0:1], v[0:1], v[16:17], v[12:13] op_sel_hi:[1,0,1]
	v_max_f32_e32 v4, 0, v4
	v_max_f32_e32 v0, 0, v0
	v_max_f32_e32 v1, 0, v1
	v_max_f32_e32 v5, 0, v5
	v_max_f32_e32 v2, 0, v2
	v_max_f32_e32 v3, 0, v3
	v_pk_fma_f32 v[6:7], v[6:7], v[16:17], v[10:11] op_sel_hi:[1,0,1]
	v_pk_mul_f32 v[0:1], v[0:1], v[0:1]
	v_pk_mul_f32 v[4:5], v[4:5], v[4:5]
	v_pk_mul_f32 v[2:3], v[2:3], v[2:3]
	v_max_f32_e32 v6, 0, v6
	v_max_f32_e32 v7, 0, v7
	v_cvt_pk_bf16_f32 v0, v0, v1
	v_cvt_pk_bf16_f32 v1, v2, v3
	v_cvt_pk_bf16_f32 v2, v4, v5
	v_lshlrev_b64 v[4:5], 13, v[26:27]
	v_pk_mul_f32 v[6:7], v[6:7], v[6:7]
	v_lshl_add_u64 v[4:5], s[12:13], 0, v[4:5]
	v_cvt_pk_bf16_f32 v3, v6, v7
	v_lshl_add_u64 v[4:5], v[24:25], 1, v[4:5]
	global_store_dwordx4 v[4:5], v[0:3], off sc1
	s_nop 1
	v_add_u32_e32 v0, 0x400, v32
	v_ashrrev_i32_e32 v1, 31, v0
	v_lshrrev_b32_e32 v1, 28, v1
	v_add_u32_e32 v1, v0, v1
	v_ashrrev_i32_e32 v8, 4, v1
	v_and_b32_e32 v1, -16, v1
	v_sub_u32_e32 v9, v0, v1
	v_add_u32_e32 v26, s11, v8
	v_lshlrev_b32_e32 v5, 1, v9
	v_ashrrev_i32_e32 v27, 31, v26
	v_lshlrev_b32_e32 v4, 9, v8
	v_and_b32_e32 v6, 15, v8
	v_bitop3_b32 v0, v5, v8, 15 bitop3:0x78
	v_lshl_add_u32 v24, v9, 3, s10
	v_lshl_add_u64 v[8:9], s[4:5], 0, v[26:27]
	v_bitop3_b32 v5, v5, v6, 1 bitop3:0x36
	v_lshlrev_b64 v[8:9], 6, v[8:9]
	v_lshl_add_u32 v0, v0, 4, v4
	v_lshl_add_u32 v4, v5, 4, v4
	v_lshl_add_u64 v[20:21], s[74:75], 0, v[8:9]
	ds_read_b128 v[0:3], v0
	ds_read_b128 v[4:7], v4
	global_load_dwordx4 v[8:11], v[20:21], off offset:48
	global_load_dwordx4 v[12:15], v[20:21], off offset:32
	global_load_dwordx4 v[16:19], v[20:21], off
	s_nop 0
	global_load_dwordx4 v[20:23], v[20:21], off offset:16
	v_ashrrev_i32_e32 v25, 31, v24
	s_waitcnt vmcnt(0)
	v_pk_add_f32 v[16:17], v[16:17], v[20:21]
	v_pk_add_f32 v[18:19], v[18:19], v[22:23]
	v_pk_add_f32 v[12:13], v[16:17], v[12:13]
	v_pk_add_f32 v[14:15], v[18:19], v[14:15]
	v_pk_add_f32 v[8:9], v[12:13], v[8:9]
	v_pk_add_f32 v[10:11], v[14:15], v[10:11]
	v_add_f32_e32 v8, v8, v9
	v_add_f32_e32 v8, v10, v8
	v_add_f32_e32 v8, v11, v8
	v_fmamk_f32 v8, v8, 0x3a800000, v208
	v_cmp_gt_f32_e32 vcc, s92, v8
	v_mul_f32_e32 v9, 0x4b800000, v8
	v_lshl_add_u64 v[12:13], v[24:25], 2, s[6:7]
	v_cndmask_b32_e32 v8, v8, v9, vcc
	v_rsq_f32_e32 v8, v8
	s_nop 0
	v_mul_f32_e32 v9, 0x45800000, v8
	v_cndmask_b32_e32 v16, v8, v9, vcc
	global_load_dwordx4 v[8:11], v[12:13], off offset:16
	s_nop 0
	global_load_dwordx4 v[12:15], v[12:13], off
	s_waitcnt vmcnt(1) lgkmcnt(0)
	v_pk_fma_f32 v[4:5], v[4:5], v[16:17], v[8:9] op_sel_hi:[1,0,1]
	s_waitcnt vmcnt(0)
	v_pk_fma_f32 v[2:3], v[2:3], v[16:17], v[14:15] op_sel_hi:[1,0,1]
	v_pk_fma_f32 v[0:1], v[0:1], v[16:17], v[12:13] op_sel_hi:[1,0,1]
	v_max_f32_e32 v4, 0, v4
	v_max_f32_e32 v0, 0, v0
	v_max_f32_e32 v1, 0, v1
	v_max_f32_e32 v5, 0, v5
	v_max_f32_e32 v2, 0, v2
	v_max_f32_e32 v3, 0, v3
	v_pk_fma_f32 v[6:7], v[6:7], v[16:17], v[10:11] op_sel_hi:[1,0,1]
	v_pk_mul_f32 v[0:1], v[0:1], v[0:1]
	v_pk_mul_f32 v[4:5], v[4:5], v[4:5]
	v_pk_mul_f32 v[2:3], v[2:3], v[2:3]
	v_max_f32_e32 v6, 0, v6
	v_max_f32_e32 v7, 0, v7
	v_cvt_pk_bf16_f32 v0, v0, v1
	v_cvt_pk_bf16_f32 v1, v2, v3
	v_cvt_pk_bf16_f32 v2, v4, v5
	v_lshlrev_b64 v[4:5], 13, v[26:27]
	v_pk_mul_f32 v[6:7], v[6:7], v[6:7]
	v_lshl_add_u64 v[4:5], s[12:13], 0, v[4:5]
	v_cvt_pk_bf16_f32 v3, v6, v7
	v_lshl_add_u64 v[4:5], v[24:25], 1, v[4:5]
	global_store_dwordx4 v[4:5], v[0:3], off sc1
	s_nop 1
	v_add_u32_e32 v0, 0x600, v32
	v_ashrrev_i32_e32 v1, 31, v0
	v_lshrrev_b32_e32 v1, 28, v1
	v_add_u32_e32 v1, v0, v1
	v_ashrrev_i32_e32 v9, 4, v1
	v_and_b32_e32 v1, -16, v1
	v_add_u32_e32 v10, s11, v9
	v_sub_u32_e32 v8, v0, v1
	v_ashrrev_i32_e32 v11, 31, v10
	v_lshlrev_b32_e32 v5, 1, v8
	v_and_b32_e32 v6, 15, v9
	v_lshl_add_u64 v[12:13], s[4:5], 0, v[10:11]
	v_lshlrev_b32_e32 v4, 9, v9
	v_bitop3_b32 v0, v5, v9, 15 bitop3:0x78
	v_bitop3_b32 v5, v5, v6, 1 bitop3:0x36
	v_lshlrev_b64 v[12:13], 6, v[12:13]
	v_lshl_add_u32 v0, v0, 4, v4
	v_lshl_add_u32 v4, v5, 4, v4
	v_lshl_add_u64 v[24:25], s[74:75], 0, v[12:13]
	ds_read_b128 v[0:3], v0
	ds_read_b128 v[4:7], v4
	global_load_dwordx4 v[12:15], v[24:25], off offset:48
	global_load_dwordx4 v[16:19], v[24:25], off offset:32
	global_load_dwordx4 v[20:23], v[24:25], off
	s_nop 0
	global_load_dwordx4 v[24:27], v[24:25], off offset:16
	v_lshl_add_u32 v8, v8, 3, s10
	s_waitcnt vmcnt(0)
	v_pk_add_f32 v[20:21], v[20:21], v[24:25]
	v_pk_add_f32 v[22:23], v[22:23], v[26:27]
	v_pk_add_f32 v[16:17], v[20:21], v[16:17]
	v_pk_add_f32 v[18:19], v[22:23], v[18:19]
	v_pk_add_f32 v[12:13], v[16:17], v[12:13]
	v_pk_add_f32 v[14:15], v[18:19], v[14:15]
	v_add_f32_e32 v9, v12, v13
	v_add_f32_e32 v9, v14, v9
	v_add_f32_e32 v9, v15, v9
	v_fmamk_f32 v9, v9, 0x3a800000, v208
	v_cmp_gt_f32_e32 vcc, s92, v9
	v_mul_f32_e32 v12, 0x4b800000, v9
	s_nop 0
	v_cndmask_b32_e32 v9, v9, v12, vcc
	v_rsq_f32_e32 v9, v9
	s_nop 0
	v_mul_f32_e32 v12, 0x45800000, v9
	v_cndmask_b32_e32 v20, v9, v12, vcc
	v_ashrrev_i32_e32 v9, 31, v8
	v_lshl_add_u64 v[16:17], v[8:9], 2, s[6:7]
	global_load_dwordx4 v[12:15], v[16:17], off offset:16
	s_nop 0
	global_load_dwordx4 v[16:19], v[16:17], off
	s_waitcnt vmcnt(1) lgkmcnt(0)
	v_pk_fma_f32 v[4:5], v[4:5], v[20:21], v[12:13] op_sel_hi:[1,0,1]
	s_waitcnt vmcnt(0)
	v_pk_fma_f32 v[2:3], v[2:3], v[20:21], v[18:19] op_sel_hi:[1,0,1]
	v_pk_fma_f32 v[0:1], v[0:1], v[20:21], v[16:17] op_sel_hi:[1,0,1]
	v_max_f32_e32 v4, 0, v4
	v_max_f32_e32 v0, 0, v0
	v_max_f32_e32 v1, 0, v1
	v_max_f32_e32 v5, 0, v5
	v_max_f32_e32 v2, 0, v2
	v_max_f32_e32 v3, 0, v3
	v_pk_fma_f32 v[6:7], v[6:7], v[20:21], v[14:15] op_sel_hi:[1,0,1]
	v_pk_mul_f32 v[0:1], v[0:1], v[0:1]
	v_pk_mul_f32 v[4:5], v[4:5], v[4:5]
	v_pk_mul_f32 v[2:3], v[2:3], v[2:3]
	v_max_f32_e32 v6, 0, v6
	v_max_f32_e32 v7, 0, v7
	v_cvt_pk_bf16_f32 v0, v0, v1
	v_cvt_pk_bf16_f32 v1, v2, v3
	v_cvt_pk_bf16_f32 v2, v4, v5
	v_lshlrev_b64 v[4:5], 13, v[10:11]
	v_pk_mul_f32 v[6:7], v[6:7], v[6:7]
	v_lshl_add_u64 v[4:5], s[12:13], 0, v[4:5]
	v_cvt_pk_bf16_f32 v3, v6, v7
	v_lshl_add_u64 v[4:5], v[8:9], 1, v[4:5]
	global_store_dwordx4 v[4:5], v[0:3], off sc1
	s_barrier
	s_load_dword s10, s[88:89], 0x0
	s_waitcnt lgkmcnt(0)
	s_add_i32 s31, s10, s31
	s_cmpk_gt_i32 s31, 0xff
	s_cbranch_scc0 .LBB0_119

; #define WAIT_V0() asm volatile("s_waitcnt vmcnt(0)" ::: "memory")
; template <int EK, int TS, int KS>
; DI void ctx_tiles(const Params& p, int l, const bf16_t* __restrict__ A, const bf16_t* __restrict__ Bt, int N, int K, ldsp_t shm) {
;     ...
;         const int tm = u / ntn, tn = u % ntn;
;         int tid = threadIdx.x;
;         asm volatile("" : "+v"(tid));
;         const int wid = tid >> 6, lane = tid & 63, wr = wid >> 2, wc = wid & 3, fr = lane & 15, fq = lane >> 4;
;         unsigned soff[PP];
; #pragma unroll
;         for (int i = 0; i < PP; ++i) { int sR, sC; stage_rc_ks<KS>((wid * PP + i) * 1024 + lane * 16, sR, sC); soff[i] = (unsigned)(sR * K + sC) * 2u; }
;         const bf16_t* Ab = A + (size_t)tm * TS * K;
;         const bf16_t* Bb = Bt + (size_t)tn * TS * K;
;     ...
;         f32x4 acc[MT][NT];
; #pragma unroll
;         for (int m = 0; m < MT; ++m)
; #pragma unroll
;             for (int n = 0; n < NT; ++n) acc[m][n] = (f32x4){0.f, 0.f, 0.f, 0.f};
;         const int aoff = lds_byte_ks<KS>(wr * WM + fr, fq * 8), boff = lds_byte_ks<KS>(wc * WN + fr, fq * 8);
;         C_STAGE(0, 0); WAIT_V0(); __syncthreads();
;         for (int t = 0; t < nt; ++t) {
;             const int cur = t & 1;
;             if (t + 1 < nt) C_STAGE(cur ^ 1, t + 1);
.LBB0_156:
	v_mov_b32_e32 v16, v252
	s_movk_i32 s6, 0x7800
	v_ashrrev_i32_e32 v0, 6, v16
	v_lshlrev_b32_e32 v1, 4, v16
	v_and_b32_e32 v2, 32, v16
	v_lshlrev_b32_e32 v22, 12, v0
	v_bitop3_b32 v1, v1, v2, 48 bitop3:0x6c
	v_lshlrev_b32_e32 v2, 9, v16
	v_and_or_b32 v1, v2, s6, v1
	v_ashrrev_i32_e32 v2, 10, v22
	v_ashrrev_i32_e32 v3, 31, v2
	v_lshrrev_b32_e32 v3, 29, v3
	v_add_u32_e32 v3, v2, v3
	s_waitcnt lgkmcnt(5)
	v_and_b32_e32 v4, 0x3fffff8, v3
	v_lshlrev_b32_e32 v3, 12, v3
	v_sub_u32_e32 v2, v2, v4
	v_and_or_b32 v3, v3, s90, v1
	s_waitcnt lgkmcnt(1)
	v_or_b32_e32 v6, 0x400, v22
	v_lshl_add_u32 v192, v2, 6, v3
	v_ashrrev_i32_e32 v2, 10, v6
	v_ashrrev_i32_e32 v3, 31, v2
	v_lshrrev_b32_e32 v3, 29, v3
	v_add_u32_e32 v3, v2, v3
	v_and_b32_e32 v4, 0x3fffff8, v3
	v_lshlrev_b32_e32 v3, 12, v3
	v_sub_u32_e32 v2, v2, v4
	v_and_or_b32 v3, v3, s90, v1
	v_or_b32_e32 v10, 0x800, v22
	v_lshl_add_u32 v8, v2, 6, v3
	v_ashrrev_i32_e32 v2, 10, v10
	v_ashrrev_i32_e32 v3, 31, v2
	s_ashr_i32 s4, s9, 31
	v_lshrrev_b32_e32 v3, 29, v3
	s_lshr_b32 s4, s4, 28
	v_add_u32_e32 v3, v2, v3
	s_add_i32 s5, s9, s4
	v_and_b32_e32 v4, 0x3fffff8, v3
	v_lshlrev_b32_e32 v3, 12, v3
	s_ashr_i32 s4, s5, 4
	v_sub_u32_e32 v2, v2, v4
	v_and_or_b32 v3, v3, s90, v1
	v_or_b32_e32 v14, 0xc00, v22
	s_and_b32 s5, s5, -16
	v_lshl_add_u32 v12, v2, 6, v3
	v_ashrrev_i32_e32 v2, 10, v14
	s_sub_i32 s42, s9, s5
	v_ashrrev_i32_e32 v3, 31, v2
	s_ashr_i32 s5, s4, 31
	s_ashr_i32 s43, s42, 31
	v_lshrrev_b32_e32 v3, 29, v3
	s_lshl_b64 s[6:7], s[4:5], 17
	s_lshl_b64 s[46:47], s[42:43], 17
	v_readlane_b32 s5, v253, 30
	v_add_u32_e32 v3, v2, v3
	s_add_u32 s6, s5, s6
	v_readlane_b32 s5, v253, 31
	v_and_b32_e32 v4, 0x3fffff8, v3
	s_addc_u32 s7, s5, s7
	v_sub_u32_e32 v2, v2, v4
	s_add_u32 s46, s93, s46
	v_readfirstlane_b32 s51, v22
	v_add_u32_e32 v4, 0x8000, v22
	s_addc_u32 s47, s98, s47
	s_mov_b32 m0, s51
	v_readfirstlane_b32 s84, v4
	v_mov_b32_e32 v9, v193
	global_load_lds_dwordx4 v192, s[6:7]
	s_mov_b32 m0, s84
	s_waitcnt lgkmcnt(0)
	v_lshl_add_u64 v[4:5], s[6:7], 0, v[8:9]
	v_readfirstlane_b32 s85, v6
	v_lshl_add_u64 v[6:7], s[46:47], 0, v[8:9]
	v_add_u32_e32 v9, 0x8400, v22
	global_load_lds_dwordx4 v192, s[46:47]
	s_mov_b32 m0, s85
	v_readfirstlane_b32 s86, v9
	global_load_lds_dwordx4 v8, s[6:7]
	s_mov_b32 m0, s86
	v_mov_b32_e32 v13, v193
	v_lshlrev_b32_e32 v3, 12, v3
	global_load_lds_dwordx4 v8, s[46:47]
	v_lshl_add_u64 v[8:9], s[6:7], 0, v[12:13]
	v_readfirstlane_b32 s87, v10
	v_lshl_add_u64 v[10:11], s[46:47], 0, v[12:13]
	v_add_u32_e32 v13, 0x8800, v22
	v_and_or_b32 v1, v3, s90, v1
	s_mov_b32 m0, s87
	v_readfirstlane_b32 s88, v13
	v_lshl_add_u32 v20, v2, 6, v1
	global_load_lds_dwordx4 v12, s[6:7]
	s_mov_b32 m0, s88
	v_mov_b32_e32 v21, v193
	v_ashrrev_i32_e32 v1, 3, v16
	global_load_lds_dwordx4 v12, s[46:47]
	v_lshl_add_u64 v[12:13], s[6:7], 0, v[20:21]
	v_readfirstlane_b32 s89, v14
	v_lshl_add_u64 v[14:15], s[46:47], 0, v[20:21]
	v_add_u32_e32 v21, 0x8c00, v22
	v_and_b32_e32 v17, 15, v16
	v_and_b32_e32 v19, 0xffffffe0, v1
	v_and_b32_e32 v1, 48, v16
	v_lshlrev_b32_e32 v23, 4, v0
	v_lshlrev_b32_e32 v0, 2, v16
	s_mov_b32 m0, s89
	v_readfirstlane_b32 s90, v21
	v_add_u32_e32 v27, 0x10000, v22
	v_lshl_or_b32 v24, v17, 6, v1
	v_and_b32_e32 v25, 32, v0
	v_lshl_add_u64 v[0:1], s[6:7], 0, v[192:193]
	global_load_lds_dwordx4 v20, s[6:7]
	s_mov_b32 m0, s90
	v_readfirstlane_b32 s5, v27
	v_add_u32_e32 v27, 0x18000, v22
	v_lshl_add_u64 v[2:3], s[46:47], 0, v[192:193]
	global_load_lds_dwordx4 v20, s[46:47]
	v_lshl_add_u64 v[20:21], v[0:1], 0, s[2:3]
	s_mov_b32 m0, s5
	v_readfirstlane_b32 s6, v27
	v_add_u32_e32 v27, 0x10400, v22
	global_load_lds_dwordx4 v[20:21], off
	v_lshl_add_u64 v[20:21], v[2:3], 0, s[2:3]
	s_mov_b32 m0, s6
	v_readfirstlane_b32 s7, v27
	v_add_u32_e32 v27, 0x18400, v22
	global_load_lds_dwordx4 v[20:21], off
	v_lshl_add_u64 v[20:21], v[4:5], 0, s[2:3]
	s_mov_b32 m0, s7
	v_readfirstlane_b32 s31, v27
	v_add_u32_e32 v27, 0x10800, v22
	global_load_lds_dwordx4 v[20:21], off
	v_lshl_add_u64 v[20:21], v[6:7], 0, s[2:3]
	s_mov_b32 m0, s31
	v_readfirstlane_b32 s45, v27
	v_add_u32_e32 v27, 0x18800, v22
	global_load_lds_dwordx4 v[20:21], off
	v_lshl_add_u64 v[20:21], v[8:9], 0, s[2:3]
	s_mov_b32 m0, s45
	v_readfirstlane_b32 s46, v27
	v_add_u32_e32 v27, 0x10c00, v22
	global_load_lds_dwordx4 v[20:21], off
	v_lshl_add_u64 v[20:21], v[10:11], 0, s[2:3]
	s_mov_b32 m0, s46
	v_readfirstlane_b32 s47, v27
	v_add_u32_e32 v22, 0x18c00, v22
	global_load_lds_dwordx4 v[20:21], off
	v_lshl_add_u64 v[20:21], v[12:13], 0, s[2:3]
	s_mov_b32 m0, s47
	v_readfirstlane_b32 s50, v22
	v_or_b32_e32 v18, v19, v17
	v_lshlrev_b32_e32 v26, 9, v19
	v_and_b32_e32 v19, 48, v23
	global_load_lds_dwordx4 v[20:21], off
	v_lshl_add_u64 v[20:21], v[14:15], 0, s[2:3]
	s_mov_b32 m0, s50
	v_lshlrev_b32_e32 v23, 9, v19
	global_load_lds_dwordx4 v[20:21], off
	v_bitop3_b32 v21, v24, v26, v25 bitop3:0xde
	v_bitop3_b32 v20, v24, v23, v25 bitop3:0xde
	s_waitcnt vmcnt(8)
	s_waitcnt vmcnt(8) lgkmcnt(0)
	s_barrier
; #define LDSP __attribute__((address_space(3)))
; #define WAIT_V0() asm volatile("s_waitcnt vmcnt(0)" ::: "memory")
; template <int EK, int TS, int KS>
; DI void ctx_tiles(const Params& p, int l, const bf16_t* __restrict__ A, const bf16_t* __restrict__ Bt, int N, int K, ldsp_t shm) {
;     ...
;         for (int t = 0; t < nt; ++t) {
;             const int cur = t & 1;
;             if (t + 1 < nt) C_STAGE(cur ^ 1, t + 1);
;             ldsp_t sa = shm + cur * 2 * TILE_A, sb = sa + TILE_A;
; #pragma unroll
;             for (int ks = 0; ks < KS; ++ks) {
;                 bf16x8 At[MT], Bf[NT];
; #pragma unroll
;                 for (int m = 0; m < MT; ++m) At[m] = *(const LDSP bf16x8*)(sa + aoff + m * (KS * 1024) + ks * 1024);
; #pragma unroll
;                 for (int n = 0; n < NT; ++n) Bf[n] = *(const LDSP bf16x8*)(sb + boff + n * (KS * 1024) + ks * 1024);
; #pragma unroll
;                 for (int m = 0; m < MT; ++m)
; #pragma unroll
;                     for (int n = 0; n < NT; ++n) acc[m][n] = __builtin_amdgcn_mfma_f32_16x16x32_bf16(Bf[n], At[m], acc[m][n], 0, 0, 0);
;             }
;             WAIT_V0(); __syncthreads();
;         }
	ds_read_b128 v[22:25], v21
	ds_read_b128 v[26:29], v21 offset:8192
	ds_read_b128 v[30:33], v20 offset:32768
	s_waitcnt lgkmcnt(0)
	v_mfma_f32_16x16x32_bf16 v[22:25], v[30:33], v[22:25], 0
	s_mov_b32 m0, s51
	v_or_b32_e32 v46, 0x18c00, v20
	v_or_b32_e32 v47, 0x19000, v20
	v_mfma_f32_16x16x32_bf16 v[26:29], v[30:33], v[26:29], 0
	ds_read_b128 v[30:33], v21 offset:1024
	ds_read_b128 v[34:37], v21 offset:9216
	ds_read_b128 v[38:41], v20 offset:33792
	v_or_b32_e32 v48, 0x19400, v20
	v_or_b32_e32 v49, 0x19800, v20
	s_waitcnt lgkmcnt(0)
	v_mfma_f32_16x16x32_bf16 v[22:25], v[38:41], v[30:33], v[22:25]
	s_mov_b64 s[10:11], 0x600
	v_or_b32_e32 v50, 0x19c00, v20
	v_mfma_f32_16x16x32_bf16 v[26:29], v[38:41], v[34:37], v[26:29]
	ds_read_b128 v[30:33], v21 offset:2048
	ds_read_b128 v[34:37], v21 offset:10240
	ds_read_b128 v[38:41], v20 offset:34816
	s_waitcnt lgkmcnt(0)
	v_mfma_f32_16x16x32_bf16 v[22:25], v[38:41], v[30:33], v[22:25]
	v_mfma_f32_16x16x32_bf16 v[26:29], v[38:41], v[34:37], v[26:29]
	ds_read_b128 v[30:33], v21 offset:3072
	ds_read_b128 v[34:37], v21 offset:11264
	ds_read_b128 v[38:41], v20 offset:35840
	s_waitcnt lgkmcnt(0)
	v_mfma_f32_16x16x32_bf16 v[22:25], v[38:41], v[30:33], v[22:25]
	v_mfma_f32_16x16x32_bf16 v[26:29], v[38:41], v[34:37], v[26:29]
	ds_read_b128 v[30:33], v21 offset:4096
	ds_read_b128 v[34:37], v21 offset:12288
	ds_read_b128 v[38:41], v20 offset:36864
	s_waitcnt lgkmcnt(0)
	v_mfma_f32_16x16x32_bf16 v[22:25], v[38:41], v[30:33], v[22:25]
	v_mfma_f32_16x16x32_bf16 v[26:29], v[38:41], v[34:37], v[26:29]
	ds_read_b128 v[30:33], v21 offset:5120
	ds_read_b128 v[34:37], v21 offset:13312
	ds_read_b128 v[38:41], v20 offset:37888
	s_waitcnt lgkmcnt(0)
	v_mfma_f32_16x16x32_bf16 v[22:25], v[38:41], v[30:33], v[22:25]
	v_mfma_f32_16x16x32_bf16 v[26:29], v[38:41], v[34:37], v[26:29]
	ds_read_b128 v[30:33], v21 offset:6144
	ds_read_b128 v[34:37], v21 offset:14336
	ds_read_b128 v[38:41], v20 offset:38912
	s_waitcnt lgkmcnt(0)
	v_mfma_f32_16x16x32_bf16 v[22:25], v[38:41], v[30:33], v[22:25]
	v_mfma_f32_16x16x32_bf16 v[26:29], v[38:41], v[34:37], v[26:29]
	ds_read_b128 v[30:33], v21 offset:7168
	ds_read_b128 v[34:37], v21 offset:15360
	ds_read_b128 v[38:41], v20 offset:39936
	s_waitcnt vmcnt(0)
	s_waitcnt vmcnt(0) lgkmcnt(0)
	v_mfma_f32_16x16x32_bf16 v[30:33], v[38:41], v[30:33], v[22:25]
	s_barrier
	s_nop 1
	v_lshl_add_u64 v[22:23], v[0:1], 0, s[24:25]
	global_load_lds_dwordx4 v[22:23], off
	v_lshl_add_u64 v[22:23], v[2:3], 0, s[24:25]
	s_mov_b32 m0, s84
	v_mfma_f32_16x16x32_bf16 v[24:27], v[38:41], v[34:37], v[26:29]
	global_load_lds_dwordx4 v[22:23], off
	v_lshl_add_u64 v[22:23], v[4:5], 0, s[24:25]
	s_mov_b32 m0, s85
	v_lshl_add_u64 v[0:1], v[0:1], 0, s[10:11]
	global_load_lds_dwordx4 v[22:23], off
	v_lshl_add_u64 v[22:23], v[6:7], 0, s[24:25]
	s_mov_b32 m0, s86
	s_nop 0
	global_load_lds_dwordx4 v[22:23], off
	v_lshl_add_u64 v[22:23], v[8:9], 0, s[24:25]
	s_mov_b32 m0, s87
	s_nop 0
	global_load_lds_dwordx4 v[22:23], off
	v_lshl_add_u64 v[22:23], v[10:11], 0, s[24:25]
	s_mov_b32 m0, s88
	s_nop 0
	global_load_lds_dwordx4 v[22:23], off
	v_lshl_add_u64 v[22:23], v[12:13], 0, s[24:25]
	s_mov_b32 m0, s89
	s_nop 0
	global_load_lds_dwordx4 v[22:23], off
	v_lshl_add_u64 v[22:23], v[14:15], 0, s[24:25]
	s_mov_b32 m0, s90
	v_readlane_b32 s12, v254, 50
	global_load_lds_dwordx4 v[22:23], off
	v_add_u32_e32 v22, 0x10000, v21
	v_or_b32_e32 v23, 0x18000, v20
	ds_read_b128 v[34:37], v22
	ds_read_b128 v[38:41], v22 offset:8192
	ds_read_b128 v[42:45], v23
	s_waitcnt lgkmcnt(0)
	v_mfma_f32_16x16x32_bf16 v[28:31], v[42:45], v[34:37], v[30:33]
	s_mov_b32 m0, s5
	v_readlane_b32 s16, v254, 54
	v_readlane_b32 s17, v254, 55
	v_mfma_f32_16x16x32_bf16 v[24:27], v[42:45], v[38:41], v[24:27]
	v_or_b32_e32 v44, 0x18400, v20
	ds_read_b128 v[32:35], v22 offset:1024
	ds_read_b128 v[36:39], v22 offset:9216
	ds_read_b128 v[40:43], v44
	v_or_b32_e32 v45, 0x18800, v20
	s_waitcnt lgkmcnt(0)
	v_mfma_f32_16x16x32_bf16 v[28:31], v[40:43], v[32:35], v[28:31]
	v_readlane_b32 s13, v254, 51
	v_readlane_b32 s14, v254, 52
	v_readlane_b32 s15, v254, 53
	v_mfma_f32_16x16x32_bf16 v[24:27], v[40:43], v[36:39], v[24:27]
	ds_read_b128 v[32:35], v22 offset:2048
	ds_read_b128 v[36:39], v22 offset:10240
	ds_read_b128 v[40:43], v45
	v_readlane_b32 s18, v254, 56
	s_waitcnt lgkmcnt(0)
	v_mfma_f32_16x16x32_bf16 v[28:31], v[40:43], v[32:35], v[28:31]
	v_readlane_b32 s19, v254, 57
	v_readlane_b32 s20, v254, 58
	v_readlane_b32 s21, v254, 59
	v_mfma_f32_16x16x32_bf16 v[24:27], v[40:43], v[36:39], v[24:27]
	ds_read_b128 v[32:35], v22 offset:3072
	ds_read_b128 v[36:39], v22 offset:11264
	ds_read_b128 v[40:43], v46
	v_readlane_b32 s22, v254, 60
	s_waitcnt lgkmcnt(0)
	v_mfma_f32_16x16x32_bf16 v[28:31], v[40:43], v[32:35], v[28:31]
	v_readlane_b32 s23, v254, 61
	v_readlane_b32 s24, v254, 62
	v_readlane_b32 s25, v254, 63
	v_mfma_f32_16x16x32_bf16 v[24:27], v[40:43], v[36:39], v[24:27]
	ds_read_b128 v[32:35], v22 offset:4096
	ds_read_b128 v[36:39], v22 offset:12288
	ds_read_b128 v[40:43], v47
	v_readlane_b32 s26, v255, 0
	s_waitcnt lgkmcnt(0)
	v_mfma_f32_16x16x32_bf16 v[28:31], v[40:43], v[32:35], v[28:31]
	v_readlane_b32 s27, v255, 1
	v_mfma_f32_16x16x32_bf16 v[24:27], v[40:43], v[36:39], v[24:27]
	ds_read_b128 v[32:35], v22 offset:5120
	ds_read_b128 v[36:39], v22 offset:13312
	ds_read_b128 v[40:43], v48
	s_waitcnt lgkmcnt(0)
	v_mfma_f32_16x16x32_bf16 v[28:31], v[40:43], v[32:35], v[28:31]
	v_mfma_f32_16x16x32_bf16 v[24:27], v[40:43], v[36:39], v[24:27]
	ds_read_b128 v[32:35], v22 offset:6144
	ds_read_b128 v[36:39], v22 offset:14336
	ds_read_b128 v[40:43], v49
	s_waitcnt lgkmcnt(0)
	v_mfma_f32_16x16x32_bf16 v[28:31], v[40:43], v[32:35], v[28:31]
	v_mfma_f32_16x16x32_bf16 v[24:27], v[40:43], v[36:39], v[24:27]
	ds_read_b128 v[32:35], v22 offset:7168
	ds_read_b128 v[36:39], v22 offset:15360
	ds_read_b128 v[40:43], v50
	s_waitcnt vmcnt(0)
	s_waitcnt vmcnt(0) lgkmcnt(0)
	s_barrier
; #define LDSP __attribute__((address_space(3)))
; #define WAIT_V0() asm volatile("s_waitcnt vmcnt(0)" ::: "memory")
; template <int EK, int TS, int KS>
; DI void ctx_tiles(const Params& p, int l, const bf16_t* __restrict__ A, const bf16_t* __restrict__ Bt, int N, int K, ldsp_t shm) {
;     ...
;         for (int t = 0; t < nt; ++t) {
;             const int cur = t & 1;
;             if (t + 1 < nt) C_STAGE(cur ^ 1, t + 1);
;             ldsp_t sa = shm + cur * 2 * TILE_A, sb = sa + TILE_A;
; #pragma unroll
;             for (int ks = 0; ks < KS; ++ks) {
;                 bf16x8 At[MT], Bf[NT];
; #pragma unroll
;                 for (int m = 0; m < MT; ++m) At[m] = *(const LDSP bf16x8*)(sa + aoff + m * (KS * 1024) + ks * 1024);
; #pragma unroll
;                 for (int n = 0; n < NT; ++n) Bf[n] = *(const LDSP bf16x8*)(sb + boff + n * (KS * 1024) + ks * 1024);
; #pragma unroll
;                 for (int m = 0; m < MT; ++m)
; #pragma unroll
;                     for (int n = 0; n < NT; ++n) acc[m][n] = __builtin_amdgcn_mfma_f32_16x16x32_bf16(Bf[n], At[m], acc[m][n], 0, 0, 0);
;             }
;             WAIT_V0(); __syncthreads();
;         }
; #pragma unroll
;         for (int m = 0; m < MT; ++m)
; #pragma unroll
;             for (int n = 0; n < NT; ++n) {
;                 const int row = wr * WM + m * 16 + fr, ch = (wc * WN + n * 16 + fq * 4) >> 2;
	global_load_lds_dwordx4 v[0:1], off
	v_lshl_add_u64 v[0:1], v[2:3], 0, s[10:11]
	s_mov_b32 m0, s6
	v_mfma_f32_16x16x32_bf16 v[28:31], v[40:43], v[32:35], v[28:31]
	global_load_lds_dwordx4 v[0:1], off
	v_lshl_add_u64 v[0:1], v[4:5], 0, s[10:11]
	s_mov_b32 m0, s7
	v_mfma_f32_16x16x32_bf16 v[24:27], v[40:43], v[36:39], v[24:27]
	global_load_lds_dwordx4 v[0:1], off
	v_lshl_add_u64 v[0:1], v[6:7], 0, s[10:11]
	s_mov_b32 m0, s31
	v_cmp_lt_i32_e64 s[6:7], v134, v203
	global_load_lds_dwordx4 v[0:1], off
	v_lshl_add_u64 v[0:1], v[8:9], 0, s[10:11]
	s_mov_b32 m0, s45
	s_nop 0
	global_load_lds_dwordx4 v[0:1], off
	v_lshl_add_u64 v[0:1], v[10:11], 0, s[10:11]
	s_mov_b32 m0, s46
	s_nop 0
	global_load_lds_dwordx4 v[0:1], off
	v_lshl_add_u64 v[0:1], v[12:13], 0, s[10:11]
	s_mov_b32 m0, s47
	s_nop 0
	global_load_lds_dwordx4 v[0:1], off
	v_lshl_add_u64 v[0:1], v[14:15], 0, s[10:11]
	s_mov_b32 m0, s50
	s_nop 0
	global_load_lds_dwordx4 v[0:1], off
	ds_read_b128 v[0:3], v21
	ds_read_b128 v[4:7], v21 offset:8192
	ds_read_b128 v[8:11], v20 offset:32768
	s_waitcnt lgkmcnt(0)
	v_mfma_f32_16x16x32_bf16 v[0:3], v[8:11], v[0:3], v[28:31]
	v_mfma_f32_16x16x32_bf16 v[4:7], v[8:11], v[4:7], v[24:27]
	ds_read_b128 v[8:11], v21 offset:1024
	ds_read_b128 v[12:15], v21 offset:9216
	s_nop 0
	ds_read_b128 v[24:27], v20 offset:33792
	s_waitcnt lgkmcnt(0)
	v_mfma_f32_16x16x32_bf16 v[0:3], v[24:27], v[8:11], v[0:3]
	v_mfma_f32_16x16x32_bf16 v[4:7], v[24:27], v[12:15], v[4:7]
	ds_read_b128 v[8:11], v21 offset:2048
	ds_read_b128 v[12:15], v21 offset:10240
	ds_read_b128 v[24:27], v20 offset:34816
	s_waitcnt lgkmcnt(0)
	v_mfma_f32_16x16x32_bf16 v[0:3], v[24:27], v[8:11], v[0:3]
	v_mfma_f32_16x16x32_bf16 v[4:7], v[24:27], v[12:15], v[4:7]
	ds_read_b128 v[8:11], v21 offset:3072
	ds_read_b128 v[12:15], v21 offset:11264
	ds_read_b128 v[24:27], v20 offset:35840
	s_waitcnt lgkmcnt(0)
	v_mfma_f32_16x16x32_bf16 v[0:3], v[24:27], v[8:11], v[0:3]
	v_mfma_f32_16x16x32_bf16 v[4:7], v[24:27], v[12:15], v[4:7]
	ds_read_b128 v[8:11], v21 offset:4096
	ds_read_b128 v[12:15], v21 offset:12288
	ds_read_b128 v[24:27], v20 offset:36864
	s_waitcnt lgkmcnt(0)
	v_mfma_f32_16x16x32_bf16 v[0:3], v[24:27], v[8:11], v[0:3]
	v_mfma_f32_16x16x32_bf16 v[4:7], v[24:27], v[12:15], v[4:7]
	ds_read_b128 v[8:11], v21 offset:5120
	ds_read_b128 v[12:15], v21 offset:13312
	ds_read_b128 v[24:27], v20 offset:37888
	s_waitcnt lgkmcnt(0)
	v_mfma_f32_16x16x32_bf16 v[0:3], v[24:27], v[8:11], v[0:3]
	v_mfma_f32_16x16x32_bf16 v[4:7], v[24:27], v[12:15], v[4:7]
	ds_read_b128 v[8:11], v21 offset:6144
	ds_read_b128 v[12:15], v21 offset:14336
	ds_read_b128 v[24:27], v20 offset:38912
	s_waitcnt lgkmcnt(0)
	v_mfma_f32_16x16x32_bf16 v[0:3], v[24:27], v[8:11], v[0:3]
	v_mfma_f32_16x16x32_bf16 v[4:7], v[24:27], v[12:15], v[4:7]
	ds_read_b128 v[8:11], v21 offset:7168
	ds_read_b128 v[12:15], v21 offset:15360
	ds_read_b128 v[24:27], v20 offset:39936
	s_waitcnt vmcnt(0)
	s_waitcnt vmcnt(0) lgkmcnt(0)
	v_mfma_f32_16x16x32_bf16 v[0:3], v[24:27], v[8:11], v[0:3]
	s_barrier
	v_mfma_f32_16x16x32_bf16 v[4:7], v[24:27], v[12:15], v[4:7]
	ds_read_b128 v[8:11], v22 offset:1024
	ds_read_b128 v[12:15], v23
	ds_read_b128 v[24:27], v22 offset:8192
	ds_read_b128 v[28:31], v22
	s_waitcnt lgkmcnt(0)
	v_mfma_f32_16x16x32_bf16 v[0:3], v[12:15], v[28:31], v[0:3]
	v_mfma_f32_16x16x32_bf16 v[4:7], v[12:15], v[24:27], v[4:7]
	ds_read_b128 v[12:15], v22 offset:9216
	ds_read_b128 v[24:27], v44
	s_waitcnt lgkmcnt(0)
	v_mfma_f32_16x16x32_bf16 v[0:3], v[24:27], v[8:11], v[0:3]
	v_mfma_f32_16x16x32_bf16 v[4:7], v[24:27], v[12:15], v[4:7]
	ds_read_b128 v[8:11], v22 offset:2048
	ds_read_b128 v[12:15], v22 offset:10240
	ds_read_b128 v[24:27], v45
	s_waitcnt lgkmcnt(0)
	v_mfma_f32_16x16x32_bf16 v[0:3], v[24:27], v[8:11], v[0:3]
	v_mfma_f32_16x16x32_bf16 v[4:7], v[24:27], v[12:15], v[4:7]
	ds_read_b128 v[8:11], v22 offset:3072
	ds_read_b128 v[12:15], v22 offset:11264
	ds_read_b128 v[24:27], v46
	s_waitcnt lgkmcnt(0)
	v_mfma_f32_16x16x32_bf16 v[0:3], v[24:27], v[8:11], v[0:3]
	v_mfma_f32_16x16x32_bf16 v[4:7], v[24:27], v[12:15], v[4:7]
	ds_read_b128 v[8:11], v22 offset:4096
	ds_read_b128 v[12:15], v22 offset:12288
	ds_read_b128 v[24:27], v47
	s_waitcnt lgkmcnt(0)
	v_mfma_f32_16x16x32_bf16 v[0:3], v[24:27], v[8:11], v[0:3]
	v_mfma_f32_16x16x32_bf16 v[4:7], v[24:27], v[12:15], v[4:7]
	ds_read_b128 v[8:11], v22 offset:5120
	ds_read_b128 v[12:15], v22 offset:13312
	ds_read_b128 v[24:27], v48
	s_waitcnt lgkmcnt(0)
	v_mfma_f32_16x16x32_bf16 v[0:3], v[24:27], v[8:11], v[0:3]
	v_mfma_f32_16x16x32_bf16 v[4:7], v[24:27], v[12:15], v[4:7]
	ds_read_b128 v[8:11], v22 offset:6144
	ds_read_b128 v[12:15], v22 offset:14336
	ds_read_b128 v[24:27], v49
	s_waitcnt lgkmcnt(0)
	v_mfma_f32_16x16x32_bf16 v[0:3], v[24:27], v[8:11], v[0:3]
	v_mfma_f32_16x16x32_bf16 v[4:7], v[24:27], v[12:15], v[4:7]
	ds_read_b128 v[8:11], v22 offset:7168
	ds_read_b128 v[12:15], v22 offset:15360
	ds_read_b128 v[20:23], v50
	s_waitcnt vmcnt(0)
	s_waitcnt lgkmcnt(0)
	v_mfma_f32_16x16x32_bf16 v[0:3], v[20:23], v[8:11], v[0:3]
	v_bfe_u32 v8, v16, 4, 2
	v_lshrrev_b32_e32 v9, 2, v19
	v_bitop3_b32 v8, v9, v17, v8 bitop3:0x36
	v_mfma_f32_16x16x32_bf16 v[4:7], v[20:23], v[12:15], v[4:7]
	v_lshlrev_b32_e32 v9, 8, v18
	v_lshl_or_b32 v8, v8, 4, v9
	s_barrier
; #define LDSP __attribute__((address_space(3)))
; template <int EK>
; DI void ctx_item(const Params& p, int l, int grow, int gcol, int slot, f32x4 s0, f32x4 s1, bool lead) {
;     ...
;         const float* gate = p.mod + ((size_t)l * 5 + 4) * 6144 + (EK == 1 ? 2 : 5) * DM + gcol;
;         float* xr = p.xc + (size_t)grow * DM + gcol;
;         const float* xs = (EK == 1 && l == 0) ? p.ctx + (size_t)grow * DM + gcol : xr;
;         const f32x4 g0 = *(const f32x4*)gate, g1 = *(const f32x4*)(gate + 4);
;         f32x4 x0 = *(const f32x4*)xs, x1 = *(const f32x4*)(xs + 4);
;         x0 += g0 * s0; x1 += g1 * s1;
;         *(f32x4*)xr = x0; *(f32x4*)(xr + 4) = x1;
;         const int ln = EK == 1 ? l : l + 1;
;         const float* gnx = (EK == 1 ? p.norm2_g : p.norm1_g) + (size_t)ln * DM + gcol;
;         const float* scn = p.mod + ((size_t)ln * 5 + 4) * 6144 + (EK == 1 ? 4 : 1) * DM + gcol;
;         const f32x4 a0 = *(const f32x4*)gnx * (1.f + *(const f32x4*)scn), a1 = *(const f32x4*)(gnx + 4) * (1.f + *(const f32x4*)(scn + 4));
;         const f32x4 y0 = x0 * a0, y1 = x1 * a1;
;         u32x4 w; w[0] = pk2(y0[0], y0[1]); w[1] = pk2(y0[2], y0[3]); w[2] = pk2(y1[0], y1[1]); w[3] = pk2(y1[2], y1[3]);
;         *(u32x4*)(p.H + (size_t)(NLAT + grow) * DM + gcol) = w;
; template <int EK, int TS, int KS>
; DI void ctx_tiles(const Params& p, int l, const bf16_t* __restrict__ A, const bf16_t* __restrict__ Bt, int N, int K, ldsp_t shm) {
;     ...
; #pragma unroll
;         for (int m = 0; m < MT; ++m)
; #pragma unroll
;             for (int n = 0; n < NT; ++n) {
;                 const int row = wr * WM + m * 16 + fr, ch = (wc * WN + n * 16 + fq * 4) >> 2;
;                 *(LDSP f32x4*)(shm + row * (TS * 4) + ((ch ^ (row & 15)) << 4)) = acc[m][n];
;             }
;         __syncthreads();
; #pragma unroll
;         for (int it = 0; it < (TS * TS / 8) / 512; ++it) {
;             const int item = it * 512 + tid, row = item / (TS / 8), c8 = item % (TS / 8);
;             const f32x4 s0 = *(const LDSP f32x4*)(shm + row * (TS * 4) + (((2 * c8) ^ (row & 15)) << 4));
;             const f32x4 s1 = *(const LDSP f32x4*)(shm + row * (TS * 4) + (((2 * c8 + 1) ^ (row & 15)) << 4));
;             ctx_item<EK>(p, l, tm * TS + row, tn * TS + c8 * 8, tn, s0, s1, c8 == 0);
;         }
;         __syncthreads();
	s_nop 0
	ds_write_b128 v8, v[0:3]
	s_nop 2
	ds_write_b128 v8, v[4:7] offset:4096
	v_ashrrev_i32_e32 v0, 31, v16
	v_lshrrev_b32_e32 v0, 29, v0
	v_add_u32_e32 v0, v16, v0
	v_ashrrev_i32_e32 v1, 3, v0
	v_and_b32_e32 v0, -8, v0
	v_sub_u32_e32 v2, v16, v0
	v_lshlrev_b32_e32 v3, 1, v2
	v_and_b32_e32 v4, 15, v1
	v_lshlrev_b32_e32 v0, 8, v1
	v_bitop3_b32 v5, v3, v1, 15 bitop3:0x78
	v_bitop3_b32 v3, v3, v4, 1 bitop3:0x36
	v_lshl_add_u32 v5, v5, 4, v0
	v_lshl_add_u32 v6, v3, 4, v0
	v_lshl_add_u32 v0, s4, 6, v1
	s_lshl_b32 s4, s42, 6
	v_lshl_add_u32 v26, v2, 3, s4
	v_cmp_eq_u32_e64 s[4:5], 0, v2
	v_ashrrev_i32_e32 v1, 31, v0
	v_cndmask_b32_e64 v2, v202, v134, s[6:7]
	v_cmp_lt_i32_e64 s[6:7], v135, v203
	v_ashrrev_i32_e32 v27, 31, v26
	v_lshlrev_b32_e32 v34, 2, v2
	v_cndmask_b32_e64 v2, v202, v135, s[6:7]
	v_lshlrev_b64 v[10:11], 12, v[0:1]
	v_lshlrev_b32_e32 v35, 2, v2
	v_xor_b32_e32 v2, 4, v202
	v_lshlrev_b64 v[30:31], 2, v[26:27]
	v_lshl_add_u64 v[12:13], s[70:71], 0, v[10:11]
	v_lshl_add_u64 v[10:11], s[16:17], 0, v[10:11]
	v_cmp_lt_i32_e64 s[6:7], v2, v203
	v_lshl_add_u64 v[32:33], v[12:13], 0, v[30:31]
	v_lshl_add_u64 v[10:11], v[10:11], 0, v[30:31]
	v_cndmask_b32_e64 v2, v202, v2, s[6:7]
	v_lshl_add_u64 v[14:15], s[36:37], 0, v[30:31]
	v_cndmask_b32_e32 v23, v33, v11, vcc
	v_cndmask_b32_e32 v22, v32, v10, vcc
	s_waitcnt lgkmcnt(0)
	s_barrier
	v_lshlrev_b32_e32 v36, 2, v2
	ds_read_b128 v[2:5], v5
	ds_read_b128 v[6:9], v6
	global_load_dwordx4 v[10:13], v[14:15], off offset:16
	s_nop 0
	global_load_dwordx4 v[14:17], v[14:15], off
	s_nop 0
	global_load_dwordx4 v[18:21], v[22:23], off offset:16
	s_nop 0
	global_load_dwordx4 v[22:25], v[22:23], off
	v_lshlrev_b64 v[28:29], 11, v[0:1]
	s_brev_b32 s6, 64
	s_waitcnt vmcnt(1) lgkmcnt(0)
	v_pk_fma_f32 v[8:9], v[8:9], v[12:13], v[20:21]
	s_waitcnt vmcnt(0)
	v_pk_fma_f32 v[4:5], v[4:5], v[16:17], v[24:25]
	v_pk_fma_f32 v[2:3], v[2:3], v[14:15], v[22:23]
	v_pk_fma_f32 v[6:7], v[6:7], v[10:11], v[18:19]
	global_store_dwordx4 v[32:33], v[2:5], off sc1
	global_store_dwordx4 v[32:33], v[6:9], off offset:16 sc1
	v_lshl_add_u64 v[14:15], s[38:39], 0, v[30:31]
	v_lshl_add_u64 v[22:23], s[40:41], 0, v[30:31]
	global_load_dwordx4 v[10:13], v[14:15], off offset:16
	s_nop 0
	global_load_dwordx4 v[14:17], v[14:15], off
	s_nop 0
	global_load_dwordx4 v[18:21], v[22:23], off offset:16
	s_nop 0
	global_load_dwordx4 v[22:25], v[22:23], off
	s_waitcnt vmcnt(1)
	v_pk_add_f32 v[20:21], v[20:21], 1.0 op_sel_hi:[1,0]
	s_waitcnt vmcnt(0)
	v_pk_add_f32 v[22:23], v[22:23], 1.0 op_sel_hi:[1,0]
	v_pk_add_f32 v[18:19], v[18:19], 1.0 op_sel_hi:[1,0]
	v_pk_mul_f32 v[14:15], v[14:15], v[22:23]
	v_pk_mul_f32 v[12:13], v[12:13], v[20:21]
	v_pk_mul_f32 v[14:15], v[2:3], v[14:15]
	v_mul_f32_e32 v3, v3, v3
	v_fmac_f32_e32 v3, v2, v2
	v_fmac_f32_e32 v3, v4, v4
	v_fmac_f32_e32 v3, v5, v5
	v_fmac_f32_e32 v3, v6, v6
	v_fmac_f32_e32 v3, v7, v7
	v_fmac_f32_e32 v3, v8, v8
	v_fmac_f32_e32 v3, v9, v9
	ds_bpermute_b32 v2, v34, v3
	v_pk_mul_f32 v[10:11], v[10:11], v[18:19]
	v_pk_add_f32 v[24:25], v[24:25], 1.0 op_sel_hi:[1,0]
	v_pk_mul_f32 v[18:19], v[8:9], v[12:13]
	v_pk_mul_f32 v[12:13], v[6:7], v[10:11]
	s_waitcnt lgkmcnt(0)
	v_add_f32_e32 v2, v3, v2
	ds_bpermute_b32 v3, v35, v2
	v_cvt_pk_bf16_f32 v10, v14, v15
	v_lshl_add_u64 v[14:15], s[82:83], 0, v[28:29]
	v_pk_mul_f32 v[16:17], v[16:17], v[24:25]
	v_lshl_add_u64 v[14:15], v[26:27], 1, v[14:15]
	s_waitcnt lgkmcnt(0)
	v_add_f32_e32 v2, v2, v3
	ds_bpermute_b32 v3, v36, v2
	v_pk_mul_f32 v[16:17], v[4:5], v[16:17]
	v_add_co_u32_e64 v14, s[6:7], s6, v14
	v_cvt_pk_bf16_f32 v11, v16, v17
	v_cvt_pk_bf16_f32 v12, v12, v13
	v_cvt_pk_bf16_f32 v13, v18, v19
	v_addc_co_u32_e64 v15, s[6:7], 0, v15, s[6:7]
	global_store_dwordx4 v[14:15], v[10:13], off sc1
	s_and_saveexec_b64 s[6:7], s[4:5]
	s_cbranch_execz .LBB0_155
	v_lshl_add_u64 v[0:1], s[34:35], 0, v[0:1]
	v_lshlrev_b64 v[0:1], 6, v[0:1]
	v_lshl_add_u64 v[0:1], s[74:75], 0, v[0:1]
	v_lshl_add_u64 v[0:1], s[42:43], 2, v[0:1]
	s_waitcnt lgkmcnt(0)
	v_add_f32_e32 v2, v2, v3
	global_store_dword v[0:1], v2, off sc1
	s_branch .LBB0_155
